# sample-row prepass v3 (k1,k5,k8,k12): W staged once per workgroup into LDS by LDS-DMA in MFMA fragment order, A fully prefetched in registers: one memory round trip
# speedup vs baseline: 1.0072x; 1.0072x over previous
.Linp1_qok:
	s_cmp_gt_u32 s29, 23
	s_cbranch_scc1 .Linp1_next
	s_add_u32 s20, s16, 0x5100000
	s_addc_u32 s21, s17, 0
	s_add_u32 s22, s16, 0x100000
	s_addc_u32 s23, s17, 0
	s_add_u32 s24, s16, 0xd400000
	s_addc_u32 s25, s17, 0
	s_and_b32 s28, s12, 7
	s_lshl_b32 s29, s29, 1
	s_add_u32 s29, s29, s6
	s_lshr_b32 s30, s29, 3
	s_mul_i32 s28, s28, 6
	s_add_u32 s30, s30, s28
	s_and_b32 s31, s29, 7
	s_lshl_b32 s33, s31, 17
	s_lshl_b32 s34, s30, 17
	v_lshlrev_b32_e32 v215, 11, v202
	v_lshl_add_u32 v215, v203, 4, v215
	v_add_u32_e32 v194, s33, v204
	v_add_u32_e32 v198, s34, v215
	v_add_u32_e32 v195, s33, v204
	v_add_u32_e32 v199, s34, v215
	v_add_u32_e32 v196, s33, v204
	v_add_u32_e32 v200, s34, v215
	v_add_u32_e32 v197, s33, v204
	v_add_u32_e32 v201, s34, v215
	v_add_u32_e32 v195, 0x8000, v195
	v_add_u32_e32 v199, 0x8000, v199
	v_add_u32_e32 v196, 0x10000, v196
	v_add_u32_e32 v200, 0x10000, v200
	v_add_u32_e32 v197, 0x18000, v197
	v_add_u32_e32 v201, 0x18000, v201
	s_mul_i32 s33, s31, 0x60000
	s_lshl_b32 s34, s30, 7
	s_add_u32 s33, s33, s34
	v_add_u32_e32 v211, s33, v209
	s_lshr_b32 s35, s30, 3
	s_and_b32 s36, s30, 7
	s_lshl_b32 s36, s36, 8
	s_mov_b32 s37, 0x3f800000
	s_mov_b32 s42, 1
	s_cmp_eq_u32 s35, 0
	s_cselect_b32 s37, 0x3e38aa3b, s37
	s_cselect_b32 s42, 0, s42
	s_cmp_eq_u32 s35, 3
	s_cselect_b32 s37, 0x3e38aa3b, s37
	s_cselect_b32 s42, 0, s42
	s_sub_u32 s43, s35, 1
	s_cmp_gt_u32 s35, 3
	s_cselect_b32 s44, 1, 0
	s_sub_u32 s43, s43, s44
	s_lshl_b32 s43, s43, 20
	s_lshl_b32 s44, s31, 17
	s_add_u32 s43, s43, s44
	s_add_u32 s43, s43, s36
	s_add_u32 s38, s40, s43
	s_addc_u32 s39, s41, 0
	s_add_u32 s38, s38, 0xd280000
	s_addc_u32 s39, s39, 0
	s_lshl_b32 s44, s4, 8
	s_add_u32 s44, s22, s44
	s_addc_u32 s45, s23, 0
	s_lshl_b32 s46, s4, 14
	s_add_i32 m0, s46, 0x0
	global_load_dwordx4 v[66:69], v194, s[20:21] offset:0
	global_load_dwordx4 v[70:73], v195, s[20:21] offset:0
	global_load_lds_dwordx4 v198, s[44:45]
	s_add_i32 m0, s46, 0x400
	global_load_dwordx4 v[74:77], v196, s[20:21] offset:0
	global_load_dwordx4 v[78:81], v197, s[20:21] offset:0
	global_load_lds_dwordx4 v199, s[44:45]
	s_add_i32 m0, s46, 0x800
	global_load_dwordx4 v[82:85], v194, s[20:21] offset:64
	global_load_dwordx4 v[86:89], v195, s[20:21] offset:64
	global_load_lds_dwordx4 v200, s[44:45]
	s_add_i32 m0, s46, 0xc00
	global_load_dwordx4 v[90:93], v196, s[20:21] offset:64
	global_load_dwordx4 v[94:97], v197, s[20:21] offset:64
	global_load_lds_dwordx4 v201, s[44:45]
	s_add_u32 s44, s44, 64
	s_addc_u32 s45, s45, 0
	s_add_i32 m0, s46, 0x1000
	global_load_dwordx4 v[98:101], v194, s[20:21] offset:128
	global_load_dwordx4 v[102:105], v195, s[20:21] offset:128
	global_load_lds_dwordx4 v198, s[44:45]
	s_add_i32 m0, s46, 0x1400
	global_load_dwordx4 v[106:109], v196, s[20:21] offset:128
	global_load_dwordx4 v[110:113], v197, s[20:21] offset:128
	global_load_lds_dwordx4 v199, s[44:45]
	s_add_i32 m0, s46, 0x1800
	global_load_dwordx4 v[114:117], v194, s[20:21] offset:192
	global_load_dwordx4 v[118:121], v195, s[20:21] offset:192
	global_load_lds_dwordx4 v200, s[44:45]
	s_add_i32 m0, s46, 0x1c00
	global_load_dwordx4 v[122:125], v196, s[20:21] offset:192
	global_load_dwordx4 v[126:129], v197, s[20:21] offset:192
	global_load_lds_dwordx4 v201, s[44:45]
	s_add_u32 s44, s44, 64
	s_addc_u32 s45, s45, 0
	s_add_i32 m0, s46, 0x2000
	global_load_dwordx4 v[130:133], v194, s[20:21] offset:256
	global_load_dwordx4 v[134:137], v195, s[20:21] offset:256
	global_load_lds_dwordx4 v198, s[44:45]
	s_add_i32 m0, s46, 0x2400
	global_load_dwordx4 v[138:141], v196, s[20:21] offset:256
	global_load_dwordx4 v[142:145], v197, s[20:21] offset:256
	global_load_lds_dwordx4 v199, s[44:45]
	s_add_i32 m0, s46, 0x2800
	global_load_dwordx4 v[146:149], v194, s[20:21] offset:320
	global_load_dwordx4 v[150:153], v195, s[20:21] offset:320
	global_load_lds_dwordx4 v200, s[44:45]
	s_add_i32 m0, s46, 0x2c00
	global_load_dwordx4 v[154:157], v196, s[20:21] offset:320
	global_load_dwordx4 v[158:161], v197, s[20:21] offset:320
	global_load_lds_dwordx4 v201, s[44:45]
	s_add_u32 s44, s44, 64
	s_addc_u32 s45, s45, 0
	s_add_i32 m0, s46, 0x3000
	global_load_dwordx4 v[162:165], v194, s[20:21] offset:384
	global_load_dwordx4 v[166:169], v195, s[20:21] offset:384
	global_load_lds_dwordx4 v198, s[44:45]
	s_add_i32 m0, s46, 0x3400
	global_load_dwordx4 v[170:173], v196, s[20:21] offset:384
	global_load_dwordx4 v[174:177], v197, s[20:21] offset:384
	global_load_lds_dwordx4 v199, s[44:45]
	s_add_i32 m0, s46, 0x3800
	global_load_dwordx4 v[178:181], v194, s[20:21] offset:448
	global_load_dwordx4 v[182:185], v195, s[20:21] offset:448
	global_load_lds_dwordx4 v200, s[44:45]
	s_add_i32 m0, s46, 0x3c00
	global_load_dwordx4 v[186:189], v196, s[20:21] offset:448
	global_load_dwordx4 v[190:193], v197, s[20:21] offset:448
	global_load_lds_dwordx4 v201, s[44:45]
	s_waitcnt vmcnt(0)
	s_barrier
	s_lshl_b32 s47, s5, 15
	v_lshl_add_u32 v214, v205, 4, s47
	ds_read_b128 v[218:221], v214 offset:0
	ds_read_b128 v[222:225], v214 offset:1024
	ds_read_b128 v[226:229], v214 offset:2048
	ds_read_b128 v[230:233], v214 offset:3072
	ds_read_b128 v[234:237], v214 offset:4096
	ds_read_b128 v[238:241], v214 offset:5120
	ds_read_b128 v[242:245], v214 offset:6144
	ds_read_b128 v[246:249], v214 offset:7168
	s_waitcnt lgkmcnt(4)
	v_mfma_f32_16x16x32_bf16 v[2:5], v[218:221], v[66:69], 0
	v_mfma_f32_16x16x32_bf16 v[6:9], v[222:225], v[66:69], 0
	v_mfma_f32_16x16x32_bf16 v[10:13], v[226:229], v[66:69], 0
	v_mfma_f32_16x16x32_bf16 v[14:17], v[230:233], v[66:69], 0
	v_mfma_f32_16x16x32_bf16 v[18:21], v[218:221], v[70:73], 0
	v_mfma_f32_16x16x32_bf16 v[22:25], v[222:225], v[70:73], 0
	v_mfma_f32_16x16x32_bf16 v[26:29], v[226:229], v[70:73], 0
	v_mfma_f32_16x16x32_bf16 v[30:33], v[230:233], v[70:73], 0
	v_mfma_f32_16x16x32_bf16 v[34:37], v[218:221], v[74:77], 0
	v_mfma_f32_16x16x32_bf16 v[38:41], v[222:225], v[74:77], 0
	v_mfma_f32_16x16x32_bf16 v[42:45], v[226:229], v[74:77], 0
	v_mfma_f32_16x16x32_bf16 v[46:49], v[230:233], v[74:77], 0
	v_mfma_f32_16x16x32_bf16 v[50:53], v[218:221], v[78:81], 0
	v_mfma_f32_16x16x32_bf16 v[54:57], v[222:225], v[78:81], 0
	v_mfma_f32_16x16x32_bf16 v[58:61], v[226:229], v[78:81], 0
	v_mfma_f32_16x16x32_bf16 v[62:65], v[230:233], v[78:81], 0
	ds_read_b128 v[218:221], v214 offset:8192
	ds_read_b128 v[222:225], v214 offset:9216
	ds_read_b128 v[226:229], v214 offset:10240
	ds_read_b128 v[230:233], v214 offset:11264
	s_waitcnt lgkmcnt(4)
	v_mfma_f32_16x16x32_bf16 v[2:5], v[234:237], v[82:85], v[2:5]
	v_mfma_f32_16x16x32_bf16 v[6:9], v[238:241], v[82:85], v[6:9]
	v_mfma_f32_16x16x32_bf16 v[10:13], v[242:245], v[82:85], v[10:13]
	v_mfma_f32_16x16x32_bf16 v[14:17], v[246:249], v[82:85], v[14:17]
	v_mfma_f32_16x16x32_bf16 v[18:21], v[234:237], v[86:89], v[18:21]
	v_mfma_f32_16x16x32_bf16 v[22:25], v[238:241], v[86:89], v[22:25]
	v_mfma_f32_16x16x32_bf16 v[26:29], v[242:245], v[86:89], v[26:29]
	v_mfma_f32_16x16x32_bf16 v[30:33], v[246:249], v[86:89], v[30:33]
	v_mfma_f32_16x16x32_bf16 v[34:37], v[234:237], v[90:93], v[34:37]
	v_mfma_f32_16x16x32_bf16 v[38:41], v[238:241], v[90:93], v[38:41]
	v_mfma_f32_16x16x32_bf16 v[42:45], v[242:245], v[90:93], v[42:45]
	v_mfma_f32_16x16x32_bf16 v[46:49], v[246:249], v[90:93], v[46:49]
	v_mfma_f32_16x16x32_bf16 v[50:53], v[234:237], v[94:97], v[50:53]
	v_mfma_f32_16x16x32_bf16 v[54:57], v[238:241], v[94:97], v[54:57]
	v_mfma_f32_16x16x32_bf16 v[58:61], v[242:245], v[94:97], v[58:61]
	v_mfma_f32_16x16x32_bf16 v[62:65], v[246:249], v[94:97], v[62:65]
	ds_read_b128 v[234:237], v214 offset:12288
	ds_read_b128 v[238:241], v214 offset:13312
	ds_read_b128 v[242:245], v214 offset:14336
	ds_read_b128 v[246:249], v214 offset:15360
	s_waitcnt lgkmcnt(4)
	v_mfma_f32_16x16x32_bf16 v[2:5], v[218:221], v[98:101], v[2:5]
	v_mfma_f32_16x16x32_bf16 v[6:9], v[222:225], v[98:101], v[6:9]
	v_mfma_f32_16x16x32_bf16 v[10:13], v[226:229], v[98:101], v[10:13]
	v_mfma_f32_16x16x32_bf16 v[14:17], v[230:233], v[98:101], v[14:17]
	v_mfma_f32_16x16x32_bf16 v[18:21], v[218:221], v[102:105], v[18:21]
	v_mfma_f32_16x16x32_bf16 v[22:25], v[222:225], v[102:105], v[22:25]
	v_mfma_f32_16x16x32_bf16 v[26:29], v[226:229], v[102:105], v[26:29]
	v_mfma_f32_16x16x32_bf16 v[30:33], v[230:233], v[102:105], v[30:33]
	v_mfma_f32_16x16x32_bf16 v[34:37], v[218:221], v[106:109], v[34:37]
	v_mfma_f32_16x16x32_bf16 v[38:41], v[222:225], v[106:109], v[38:41]
	v_mfma_f32_16x16x32_bf16 v[42:45], v[226:229], v[106:109], v[42:45]
	v_mfma_f32_16x16x32_bf16 v[46:49], v[230:233], v[106:109], v[46:49]
	v_mfma_f32_16x16x32_bf16 v[50:53], v[218:221], v[110:113], v[50:53]
	v_mfma_f32_16x16x32_bf16 v[54:57], v[222:225], v[110:113], v[54:57]
	v_mfma_f32_16x16x32_bf16 v[58:61], v[226:229], v[110:113], v[58:61]
	v_mfma_f32_16x16x32_bf16 v[62:65], v[230:233], v[110:113], v[62:65]
	ds_read_b128 v[218:221], v214 offset:16384
	ds_read_b128 v[222:225], v214 offset:17408
	ds_read_b128 v[226:229], v214 offset:18432
	ds_read_b128 v[230:233], v214 offset:19456
	s_waitcnt lgkmcnt(4)
	v_mfma_f32_16x16x32_bf16 v[2:5], v[234:237], v[114:117], v[2:5]
	v_mfma_f32_16x16x32_bf16 v[6:9], v[238:241], v[114:117], v[6:9]
	v_mfma_f32_16x16x32_bf16 v[10:13], v[242:245], v[114:117], v[10:13]
	v_mfma_f32_16x16x32_bf16 v[14:17], v[246:249], v[114:117], v[14:17]
	v_mfma_f32_16x16x32_bf16 v[18:21], v[234:237], v[118:121], v[18:21]
	v_mfma_f32_16x16x32_bf16 v[22:25], v[238:241], v[118:121], v[22:25]
	v_mfma_f32_16x16x32_bf16 v[26:29], v[242:245], v[118:121], v[26:29]
	v_mfma_f32_16x16x32_bf16 v[30:33], v[246:249], v[118:121], v[30:33]
	v_mfma_f32_16x16x32_bf16 v[34:37], v[234:237], v[122:125], v[34:37]
	v_mfma_f32_16x16x32_bf16 v[38:41], v[238:241], v[122:125], v[38:41]
	v_mfma_f32_16x16x32_bf16 v[42:45], v[242:245], v[122:125], v[42:45]
	v_mfma_f32_16x16x32_bf16 v[46:49], v[246:249], v[122:125], v[46:49]
	v_mfma_f32_16x16x32_bf16 v[50:53], v[234:237], v[126:129], v[50:53]
	v_mfma_f32_16x16x32_bf16 v[54:57], v[238:241], v[126:129], v[54:57]
	v_mfma_f32_16x16x32_bf16 v[58:61], v[242:245], v[126:129], v[58:61]
	v_mfma_f32_16x16x32_bf16 v[62:65], v[246:249], v[126:129], v[62:65]
	ds_read_b128 v[234:237], v214 offset:20480
	ds_read_b128 v[238:241], v214 offset:21504
	ds_read_b128 v[242:245], v214 offset:22528
	ds_read_b128 v[246:249], v214 offset:23552
	s_waitcnt lgkmcnt(4)
	v_mfma_f32_16x16x32_bf16 v[2:5], v[218:221], v[130:133], v[2:5]
	v_mfma_f32_16x16x32_bf16 v[6:9], v[222:225], v[130:133], v[6:9]
	v_mfma_f32_16x16x32_bf16 v[10:13], v[226:229], v[130:133], v[10:13]
	v_mfma_f32_16x16x32_bf16 v[14:17], v[230:233], v[130:133], v[14:17]
	v_mfma_f32_16x16x32_bf16 v[18:21], v[218:221], v[134:137], v[18:21]
	v_mfma_f32_16x16x32_bf16 v[22:25], v[222:225], v[134:137], v[22:25]
	v_mfma_f32_16x16x32_bf16 v[26:29], v[226:229], v[134:137], v[26:29]
	v_mfma_f32_16x16x32_bf16 v[30:33], v[230:233], v[134:137], v[30:33]
	v_mfma_f32_16x16x32_bf16 v[34:37], v[218:221], v[138:141], v[34:37]
	v_mfma_f32_16x16x32_bf16 v[38:41], v[222:225], v[138:141], v[38:41]
	v_mfma_f32_16x16x32_bf16 v[42:45], v[226:229], v[138:141], v[42:45]
	v_mfma_f32_16x16x32_bf16 v[46:49], v[230:233], v[138:141], v[46:49]
	v_mfma_f32_16x16x32_bf16 v[50:53], v[218:221], v[142:145], v[50:53]
	v_mfma_f32_16x16x32_bf16 v[54:57], v[222:225], v[142:145], v[54:57]
	v_mfma_f32_16x16x32_bf16 v[58:61], v[226:229], v[142:145], v[58:61]
	v_mfma_f32_16x16x32_bf16 v[62:65], v[230:233], v[142:145], v[62:65]
	ds_read_b128 v[218:221], v214 offset:24576
	ds_read_b128 v[222:225], v214 offset:25600
	ds_read_b128 v[226:229], v214 offset:26624
	ds_read_b128 v[230:233], v214 offset:27648
	s_waitcnt lgkmcnt(4)
	v_mfma_f32_16x16x32_bf16 v[2:5], v[234:237], v[146:149], v[2:5]
	v_mfma_f32_16x16x32_bf16 v[6:9], v[238:241], v[146:149], v[6:9]
	v_mfma_f32_16x16x32_bf16 v[10:13], v[242:245], v[146:149], v[10:13]
	v_mfma_f32_16x16x32_bf16 v[14:17], v[246:249], v[146:149], v[14:17]
	v_mfma_f32_16x16x32_bf16 v[18:21], v[234:237], v[150:153], v[18:21]
	v_mfma_f32_16x16x32_bf16 v[22:25], v[238:241], v[150:153], v[22:25]
	v_mfma_f32_16x16x32_bf16 v[26:29], v[242:245], v[150:153], v[26:29]
	v_mfma_f32_16x16x32_bf16 v[30:33], v[246:249], v[150:153], v[30:33]
	v_mfma_f32_16x16x32_bf16 v[34:37], v[234:237], v[154:157], v[34:37]
	v_mfma_f32_16x16x32_bf16 v[38:41], v[238:241], v[154:157], v[38:41]
	v_mfma_f32_16x16x32_bf16 v[42:45], v[242:245], v[154:157], v[42:45]
	v_mfma_f32_16x16x32_bf16 v[46:49], v[246:249], v[154:157], v[46:49]
	v_mfma_f32_16x16x32_bf16 v[50:53], v[234:237], v[158:161], v[50:53]
	v_mfma_f32_16x16x32_bf16 v[54:57], v[238:241], v[158:161], v[54:57]
	v_mfma_f32_16x16x32_bf16 v[58:61], v[242:245], v[158:161], v[58:61]
	v_mfma_f32_16x16x32_bf16 v[62:65], v[246:249], v[158:161], v[62:65]
	ds_read_b128 v[234:237], v214 offset:28672
	ds_read_b128 v[238:241], v214 offset:29696
	ds_read_b128 v[242:245], v214 offset:30720
	ds_read_b128 v[246:249], v214 offset:31744
	s_waitcnt lgkmcnt(4)
	v_mfma_f32_16x16x32_bf16 v[2:5], v[218:221], v[162:165], v[2:5]
	v_mfma_f32_16x16x32_bf16 v[6:9], v[222:225], v[162:165], v[6:9]
	v_mfma_f32_16x16x32_bf16 v[10:13], v[226:229], v[162:165], v[10:13]
	v_mfma_f32_16x16x32_bf16 v[14:17], v[230:233], v[162:165], v[14:17]
	v_mfma_f32_16x16x32_bf16 v[18:21], v[218:221], v[166:169], v[18:21]
	v_mfma_f32_16x16x32_bf16 v[22:25], v[222:225], v[166:169], v[22:25]
	v_mfma_f32_16x16x32_bf16 v[26:29], v[226:229], v[166:169], v[26:29]
	v_mfma_f32_16x16x32_bf16 v[30:33], v[230:233], v[166:169], v[30:33]
	v_mfma_f32_16x16x32_bf16 v[34:37], v[218:221], v[170:173], v[34:37]
	v_mfma_f32_16x16x32_bf16 v[38:41], v[222:225], v[170:173], v[38:41]
	v_mfma_f32_16x16x32_bf16 v[42:45], v[226:229], v[170:173], v[42:45]
	v_mfma_f32_16x16x32_bf16 v[46:49], v[230:233], v[170:173], v[46:49]
	v_mfma_f32_16x16x32_bf16 v[50:53], v[218:221], v[174:177], v[50:53]
	v_mfma_f32_16x16x32_bf16 v[54:57], v[222:225], v[174:177], v[54:57]
	v_mfma_f32_16x16x32_bf16 v[58:61], v[226:229], v[174:177], v[58:61]
	v_mfma_f32_16x16x32_bf16 v[62:65], v[230:233], v[174:177], v[62:65]
	s_waitcnt lgkmcnt(0)
	v_mfma_f32_16x16x32_bf16 v[2:5], v[234:237], v[178:181], v[2:5]
	v_mfma_f32_16x16x32_bf16 v[6:9], v[238:241], v[178:181], v[6:9]
	v_mfma_f32_16x16x32_bf16 v[10:13], v[242:245], v[178:181], v[10:13]
	v_mfma_f32_16x16x32_bf16 v[14:17], v[246:249], v[178:181], v[14:17]
	v_mfma_f32_16x16x32_bf16 v[18:21], v[234:237], v[182:185], v[18:21]
	v_mfma_f32_16x16x32_bf16 v[22:25], v[238:241], v[182:185], v[22:25]
	v_mfma_f32_16x16x32_bf16 v[26:29], v[242:245], v[182:185], v[26:29]
	v_mfma_f32_16x16x32_bf16 v[30:33], v[246:249], v[182:185], v[30:33]
	v_mfma_f32_16x16x32_bf16 v[34:37], v[234:237], v[186:189], v[34:37]
	v_mfma_f32_16x16x32_bf16 v[38:41], v[238:241], v[186:189], v[38:41]
	v_mfma_f32_16x16x32_bf16 v[42:45], v[242:245], v[186:189], v[42:45]
	v_mfma_f32_16x16x32_bf16 v[46:49], v[246:249], v[186:189], v[46:49]
	v_mfma_f32_16x16x32_bf16 v[50:53], v[234:237], v[190:193], v[50:53]
	v_mfma_f32_16x16x32_bf16 v[54:57], v[238:241], v[190:193], v[54:57]
	v_mfma_f32_16x16x32_bf16 v[58:61], v[242:245], v[190:193], v[58:61]
	v_mfma_f32_16x16x32_bf16 v[62:65], v[246:249], v[190:193], v[62:65]
	s_nop 7
	s_barrier
	ds_write_b128 v206, v[2:5] offset:0
	ds_write_b128 v206, v[6:9] offset:1024
	ds_write_b128 v206, v[10:13] offset:2048
	ds_write_b128 v206, v[14:17] offset:3072
	ds_write_b128 v206, v[18:21] offset:4096
	ds_write_b128 v206, v[22:25] offset:5120
	ds_write_b128 v206, v[26:29] offset:6144
	ds_write_b128 v206, v[30:33] offset:7168
	ds_write_b128 v206, v[34:37] offset:8192
	ds_write_b128 v206, v[38:41] offset:9216
	ds_write_b128 v206, v[42:45] offset:10240
	ds_write_b128 v206, v[46:49] offset:11264
	ds_write_b128 v206, v[50:53] offset:12288
	ds_write_b128 v206, v[54:57] offset:13312
	ds_write_b128 v206, v[58:61] offset:14336
	ds_write_b128 v206, v[62:65] offset:15360
	s_waitcnt lgkmcnt(0)
	s_barrier
	ds_read_b128 v[2:5], v207 offset:0
	ds_read_b128 v[6:9], v207 offset:16384
	ds_read_b128 v[10:13], v207 offset:32768
	ds_read_b128 v[14:17], v207 offset:49152
	ds_read_b128 v[18:21], v207 offset:1024
	ds_read_b128 v[22:25], v207 offset:17408
	ds_read_b128 v[26:29], v207 offset:33792
	ds_read_b128 v[30:33], v207 offset:50176
	ds_read_b128 v[34:37], v207 offset:2048
	ds_read_b128 v[38:41], v207 offset:18432
	ds_read_b128 v[42:45], v207 offset:34816
	ds_read_b128 v[46:49], v207 offset:51200
	ds_read_b128 v[50:53], v207 offset:3072
	ds_read_b128 v[54:57], v207 offset:19456
	ds_read_b128 v[58:61], v207 offset:35840
	ds_read_b128 v[62:65], v207 offset:52224
	s_waitcnt lgkmcnt(12)
	v_add_f32_e32 v2, v2, v6
	v_add_f32_e32 v3, v3, v7
	v_add_f32_e32 v4, v4, v8
	v_add_f32_e32 v5, v5, v9
	v_add_f32_e32 v10, v10, v14
	v_add_f32_e32 v11, v11, v15
	v_add_f32_e32 v12, v12, v16
	v_add_f32_e32 v13, v13, v17
	v_add_f32_e32 v2, v2, v10
	v_add_f32_e32 v3, v3, v11
	v_add_f32_e32 v4, v4, v12
	v_add_f32_e32 v5, v5, v13
	s_waitcnt lgkmcnt(8)
	v_add_f32_e32 v18, v18, v22
	v_add_f32_e32 v19, v19, v23
	v_add_f32_e32 v20, v20, v24
	v_add_f32_e32 v21, v21, v25
	v_add_f32_e32 v26, v26, v30
	v_add_f32_e32 v27, v27, v31
	v_add_f32_e32 v28, v28, v32
	v_add_f32_e32 v29, v29, v33
	v_add_f32_e32 v18, v18, v26
	v_add_f32_e32 v19, v19, v27
	v_add_f32_e32 v20, v20, v28
	v_add_f32_e32 v21, v21, v29
	s_waitcnt lgkmcnt(4)
	v_add_f32_e32 v34, v34, v38
	v_add_f32_e32 v35, v35, v39
	v_add_f32_e32 v36, v36, v40
	v_add_f32_e32 v37, v37, v41
	v_add_f32_e32 v42, v42, v46
	v_add_f32_e32 v43, v43, v47
	v_add_f32_e32 v44, v44, v48
	v_add_f32_e32 v45, v45, v49
	v_add_f32_e32 v34, v34, v42
	v_add_f32_e32 v35, v35, v43
	v_add_f32_e32 v36, v36, v44
	v_add_f32_e32 v37, v37, v45
	s_waitcnt lgkmcnt(0)
	v_add_f32_e32 v50, v50, v54
	v_add_f32_e32 v51, v51, v55
	v_add_f32_e32 v52, v52, v56
	v_add_f32_e32 v53, v53, v57
	v_add_f32_e32 v58, v58, v62
	v_add_f32_e32 v59, v59, v63
	v_add_f32_e32 v60, v60, v64
	v_add_f32_e32 v61, v61, v65
	v_add_f32_e32 v50, v50, v58
	v_add_f32_e32 v51, v51, v59
	v_add_f32_e32 v52, v52, v60
	v_add_f32_e32 v53, v53, v61
	s_cmp_eq_u32 s42, 0
	s_cbranch_scc1 .Linp1_nof32
	global_store_dwordx4 v210, v[2:5], s[38:39] offset:0
	global_store_dwordx4 v210, v[18:21], s[38:39] offset:64
	global_store_dwordx4 v210, v[34:37], s[38:39] offset:128
	global_store_dwordx4 v210, v[50:53], s[38:39] offset:192
	s_nop 1

	.amdhsa_kernel _Z10fwd_kernelILi1ELi2EEv4Args
		.amdhsa_group_segment_fixed_size 0
		.amdhsa_private_segment_fixed_size 0
		.amdhsa_kernarg_size 488
		.amdhsa_user_sgpr_count 2
		.amdhsa_user_sgpr_dispatch_ptr 0
		.amdhsa_user_sgpr_queue_ptr 0
		.amdhsa_user_sgpr_kernarg_segment_ptr 1
		.amdhsa_user_sgpr_dispatch_id 0
		.amdhsa_user_sgpr_kernarg_preload_length 0
		.amdhsa_user_sgpr_kernarg_preload_offset 0
		.amdhsa_user_sgpr_private_segment_size 0
		.amdhsa_uses_dynamic_stack 0
		.amdhsa_enable_private_segment 0
		.amdhsa_system_sgpr_workgroup_id_x 1
		.amdhsa_system_sgpr_workgroup_id_y 0
		.amdhsa_system_sgpr_workgroup_id_z 0
		.amdhsa_system_sgpr_workgroup_info 0
		.amdhsa_system_vgpr_workitem_id 0
		.amdhsa_next_free_vgpr 256
		.amdhsa_next_free_sgpr 58
		.amdhsa_accum_offset 256
		.amdhsa_reserve_vcc 1
		.amdhsa_float_round_mode_32 0
		.amdhsa_float_round_mode_16_64 0
		.amdhsa_float_denorm_mode_32 3
		.amdhsa_float_denorm_mode_16_64 3
		.amdhsa_dx10_clamp 1
		.amdhsa_ieee_mode 1
		.amdhsa_fp16_overflow 0
		.amdhsa_tg_split 0
		.amdhsa_exception_fp_ieee_invalid_op 0
		.amdhsa_exception_fp_denorm_src 0
		.amdhsa_exception_fp_ieee_div_zero 0
		.amdhsa_exception_fp_ieee_overflow 0
		.amdhsa_exception_fp_ieee_underflow 0
		.amdhsa_exception_fp_ieee_inexact 0
		.amdhsa_exception_int_div_zero 0
	.end_amdhsa_kernel

.Lsmp5_unit:
	s_add_u32 s20, s16, 0x5100000
	s_addc_u32 s21, s17, 0
	s_add_u32 s22, s16, 0x900000
	s_addc_u32 s23, s17, 0
	s_add_u32 s24, s16, 0xf400000
	s_addc_u32 s25, s17, 0
	s_and_b32 s28, s12, 7
	s_lshr_b32 s29, s12, 3
	s_lshl_b32 s29, s29, 1
	s_add_u32 s29, s29, s6
	s_lshr_b32 s30, s29, 3
	s_lshl_b32 s28, s28, 3
	s_add_u32 s30, s30, s28
	s_and_b32 s31, s29, 7
	s_lshl_b32 s33, s31, 17
	s_lshl_b32 s34, s30, 17
	v_lshlrev_b32_e32 v215, 11, v202
	v_lshl_add_u32 v215, v203, 4, v215
	v_add_u32_e32 v194, s33, v204
	v_add_u32_e32 v198, s34, v215
	v_add_u32_e32 v195, s33, v204
	v_add_u32_e32 v199, s34, v215
	v_add_u32_e32 v196, s33, v204
	v_add_u32_e32 v200, s34, v215
	v_add_u32_e32 v197, s33, v204
	v_add_u32_e32 v201, s34, v215
	v_add_u32_e32 v195, 0x8000, v195
	v_add_u32_e32 v199, 0x8000, v199
	v_add_u32_e32 v196, 0x10000, v196
	v_add_u32_e32 v200, 0x10000, v200
	v_add_u32_e32 v197, 0x18000, v197
	v_add_u32_e32 v201, 0x18000, v201
	s_lshl_b32 s33, s31, 19
	s_lshl_b32 s34, s30, 7
	s_add_u32 s33, s33, s34
	v_add_u32_e32 v209, s33, v208
	s_lshl_b32 s44, s4, 8
	s_add_u32 s44, s22, s44
	s_addc_u32 s45, s23, 0
	s_lshl_b32 s46, s4, 14
	s_add_i32 m0, s46, 0x0
	global_load_dwordx4 v[66:69], v194, s[20:21] offset:0
	global_load_dwordx4 v[70:73], v195, s[20:21] offset:0
	global_load_lds_dwordx4 v198, s[44:45]
	s_add_i32 m0, s46, 0x400
	global_load_dwordx4 v[74:77], v196, s[20:21] offset:0
	global_load_dwordx4 v[78:81], v197, s[20:21] offset:0
	global_load_lds_dwordx4 v199, s[44:45]
	s_add_i32 m0, s46, 0x800
	global_load_dwordx4 v[82:85], v194, s[20:21] offset:64
	global_load_dwordx4 v[86:89], v195, s[20:21] offset:64
	global_load_lds_dwordx4 v200, s[44:45]
	s_add_i32 m0, s46, 0xc00
	global_load_dwordx4 v[90:93], v196, s[20:21] offset:64
	global_load_dwordx4 v[94:97], v197, s[20:21] offset:64
	global_load_lds_dwordx4 v201, s[44:45]
	s_add_u32 s44, s44, 64
	s_addc_u32 s45, s45, 0
	s_add_i32 m0, s46, 0x1000
	global_load_dwordx4 v[98:101], v194, s[20:21] offset:128
	global_load_dwordx4 v[102:105], v195, s[20:21] offset:128
	global_load_lds_dwordx4 v198, s[44:45]
	s_add_i32 m0, s46, 0x1400
	global_load_dwordx4 v[106:109], v196, s[20:21] offset:128
	global_load_dwordx4 v[110:113], v197, s[20:21] offset:128
	global_load_lds_dwordx4 v199, s[44:45]
	s_add_i32 m0, s46, 0x1800
	global_load_dwordx4 v[114:117], v194, s[20:21] offset:192
	global_load_dwordx4 v[118:121], v195, s[20:21] offset:192
	global_load_lds_dwordx4 v200, s[44:45]
	s_add_i32 m0, s46, 0x1c00
	global_load_dwordx4 v[122:125], v196, s[20:21] offset:192
	global_load_dwordx4 v[126:129], v197, s[20:21] offset:192
	global_load_lds_dwordx4 v201, s[44:45]
	s_add_u32 s44, s44, 64
	s_addc_u32 s45, s45, 0
	s_add_i32 m0, s46, 0x2000
	global_load_dwordx4 v[130:133], v194, s[20:21] offset:256
	global_load_dwordx4 v[134:137], v195, s[20:21] offset:256
	global_load_lds_dwordx4 v198, s[44:45]
	s_add_i32 m0, s46, 0x2400
	global_load_dwordx4 v[138:141], v196, s[20:21] offset:256
	global_load_dwordx4 v[142:145], v197, s[20:21] offset:256
	global_load_lds_dwordx4 v199, s[44:45]
	s_add_i32 m0, s46, 0x2800
	global_load_dwordx4 v[146:149], v194, s[20:21] offset:320
	global_load_dwordx4 v[150:153], v195, s[20:21] offset:320
	global_load_lds_dwordx4 v200, s[44:45]
	s_add_i32 m0, s46, 0x2c00
	global_load_dwordx4 v[154:157], v196, s[20:21] offset:320
	global_load_dwordx4 v[158:161], v197, s[20:21] offset:320
	global_load_lds_dwordx4 v201, s[44:45]
	s_add_u32 s44, s44, 64
	s_addc_u32 s45, s45, 0
	s_add_i32 m0, s46, 0x3000
	global_load_dwordx4 v[162:165], v194, s[20:21] offset:384
	global_load_dwordx4 v[166:169], v195, s[20:21] offset:384
	global_load_lds_dwordx4 v198, s[44:45]
	s_add_i32 m0, s46, 0x3400
	global_load_dwordx4 v[170:173], v196, s[20:21] offset:384
	global_load_dwordx4 v[174:177], v197, s[20:21] offset:384
	global_load_lds_dwordx4 v199, s[44:45]
	s_add_i32 m0, s46, 0x3800
	global_load_dwordx4 v[178:181], v194, s[20:21] offset:448
	global_load_dwordx4 v[182:185], v195, s[20:21] offset:448
	global_load_lds_dwordx4 v200, s[44:45]
	s_add_i32 m0, s46, 0x3c00
	global_load_dwordx4 v[186:189], v196, s[20:21] offset:448
	global_load_dwordx4 v[190:193], v197, s[20:21] offset:448
	global_load_lds_dwordx4 v201, s[44:45]
	s_waitcnt vmcnt(0)
	s_barrier
	s_lshl_b32 s47, s5, 15
	v_lshl_add_u32 v214, v205, 4, s47
	ds_read_b128 v[218:221], v214 offset:0
	ds_read_b128 v[222:225], v214 offset:1024
	ds_read_b128 v[226:229], v214 offset:2048
	ds_read_b128 v[230:233], v214 offset:3072
	ds_read_b128 v[234:237], v214 offset:4096
	ds_read_b128 v[238:241], v214 offset:5120
	ds_read_b128 v[242:245], v214 offset:6144
	ds_read_b128 v[246:249], v214 offset:7168
	s_waitcnt lgkmcnt(4)
	v_mfma_f32_16x16x32_bf16 v[2:5], v[218:221], v[66:69], 0
	v_mfma_f32_16x16x32_bf16 v[6:9], v[222:225], v[66:69], 0
	v_mfma_f32_16x16x32_bf16 v[10:13], v[226:229], v[66:69], 0
	v_mfma_f32_16x16x32_bf16 v[14:17], v[230:233], v[66:69], 0
	v_mfma_f32_16x16x32_bf16 v[18:21], v[218:221], v[70:73], 0
	v_mfma_f32_16x16x32_bf16 v[22:25], v[222:225], v[70:73], 0
	v_mfma_f32_16x16x32_bf16 v[26:29], v[226:229], v[70:73], 0
	v_mfma_f32_16x16x32_bf16 v[30:33], v[230:233], v[70:73], 0
	v_mfma_f32_16x16x32_bf16 v[34:37], v[218:221], v[74:77], 0
	v_mfma_f32_16x16x32_bf16 v[38:41], v[222:225], v[74:77], 0
	v_mfma_f32_16x16x32_bf16 v[42:45], v[226:229], v[74:77], 0
	v_mfma_f32_16x16x32_bf16 v[46:49], v[230:233], v[74:77], 0
	v_mfma_f32_16x16x32_bf16 v[50:53], v[218:221], v[78:81], 0
	v_mfma_f32_16x16x32_bf16 v[54:57], v[222:225], v[78:81], 0
	v_mfma_f32_16x16x32_bf16 v[58:61], v[226:229], v[78:81], 0
	v_mfma_f32_16x16x32_bf16 v[62:65], v[230:233], v[78:81], 0
	ds_read_b128 v[218:221], v214 offset:8192
	ds_read_b128 v[222:225], v214 offset:9216
	ds_read_b128 v[226:229], v214 offset:10240
	ds_read_b128 v[230:233], v214 offset:11264
	s_waitcnt lgkmcnt(4)
	v_mfma_f32_16x16x32_bf16 v[2:5], v[234:237], v[82:85], v[2:5]
	v_mfma_f32_16x16x32_bf16 v[6:9], v[238:241], v[82:85], v[6:9]
	v_mfma_f32_16x16x32_bf16 v[10:13], v[242:245], v[82:85], v[10:13]
	v_mfma_f32_16x16x32_bf16 v[14:17], v[246:249], v[82:85], v[14:17]
	v_mfma_f32_16x16x32_bf16 v[18:21], v[234:237], v[86:89], v[18:21]
	v_mfma_f32_16x16x32_bf16 v[22:25], v[238:241], v[86:89], v[22:25]
	v_mfma_f32_16x16x32_bf16 v[26:29], v[242:245], v[86:89], v[26:29]
	v_mfma_f32_16x16x32_bf16 v[30:33], v[246:249], v[86:89], v[30:33]
	v_mfma_f32_16x16x32_bf16 v[34:37], v[234:237], v[90:93], v[34:37]
	v_mfma_f32_16x16x32_bf16 v[38:41], v[238:241], v[90:93], v[38:41]
	v_mfma_f32_16x16x32_bf16 v[42:45], v[242:245], v[90:93], v[42:45]
	v_mfma_f32_16x16x32_bf16 v[46:49], v[246:249], v[90:93], v[46:49]
	v_mfma_f32_16x16x32_bf16 v[50:53], v[234:237], v[94:97], v[50:53]
	v_mfma_f32_16x16x32_bf16 v[54:57], v[238:241], v[94:97], v[54:57]
	v_mfma_f32_16x16x32_bf16 v[58:61], v[242:245], v[94:97], v[58:61]
	v_mfma_f32_16x16x32_bf16 v[62:65], v[246:249], v[94:97], v[62:65]
	ds_read_b128 v[234:237], v214 offset:12288
	ds_read_b128 v[238:241], v214 offset:13312
	ds_read_b128 v[242:245], v214 offset:14336
	ds_read_b128 v[246:249], v214 offset:15360
	s_waitcnt lgkmcnt(4)
	v_mfma_f32_16x16x32_bf16 v[2:5], v[218:221], v[98:101], v[2:5]
	v_mfma_f32_16x16x32_bf16 v[6:9], v[222:225], v[98:101], v[6:9]
	v_mfma_f32_16x16x32_bf16 v[10:13], v[226:229], v[98:101], v[10:13]
	v_mfma_f32_16x16x32_bf16 v[14:17], v[230:233], v[98:101], v[14:17]
	v_mfma_f32_16x16x32_bf16 v[18:21], v[218:221], v[102:105], v[18:21]
	v_mfma_f32_16x16x32_bf16 v[22:25], v[222:225], v[102:105], v[22:25]
	v_mfma_f32_16x16x32_bf16 v[26:29], v[226:229], v[102:105], v[26:29]
	v_mfma_f32_16x16x32_bf16 v[30:33], v[230:233], v[102:105], v[30:33]
	v_mfma_f32_16x16x32_bf16 v[34:37], v[218:221], v[106:109], v[34:37]
	v_mfma_f32_16x16x32_bf16 v[38:41], v[222:225], v[106:109], v[38:41]
	v_mfma_f32_16x16x32_bf16 v[42:45], v[226:229], v[106:109], v[42:45]
	v_mfma_f32_16x16x32_bf16 v[46:49], v[230:233], v[106:109], v[46:49]
	v_mfma_f32_16x16x32_bf16 v[50:53], v[218:221], v[110:113], v[50:53]
	v_mfma_f32_16x16x32_bf16 v[54:57], v[222:225], v[110:113], v[54:57]
	v_mfma_f32_16x16x32_bf16 v[58:61], v[226:229], v[110:113], v[58:61]
	v_mfma_f32_16x16x32_bf16 v[62:65], v[230:233], v[110:113], v[62:65]
	ds_read_b128 v[218:221], v214 offset:16384
	ds_read_b128 v[222:225], v214 offset:17408
	ds_read_b128 v[226:229], v214 offset:18432
	ds_read_b128 v[230:233], v214 offset:19456
	s_waitcnt lgkmcnt(4)
	v_mfma_f32_16x16x32_bf16 v[2:5], v[234:237], v[114:117], v[2:5]
	v_mfma_f32_16x16x32_bf16 v[6:9], v[238:241], v[114:117], v[6:9]
	v_mfma_f32_16x16x32_bf16 v[10:13], v[242:245], v[114:117], v[10:13]
	v_mfma_f32_16x16x32_bf16 v[14:17], v[246:249], v[114:117], v[14:17]
	v_mfma_f32_16x16x32_bf16 v[18:21], v[234:237], v[118:121], v[18:21]
	v_mfma_f32_16x16x32_bf16 v[22:25], v[238:241], v[118:121], v[22:25]
	v_mfma_f32_16x16x32_bf16 v[26:29], v[242:245], v[118:121], v[26:29]
	v_mfma_f32_16x16x32_bf16 v[30:33], v[246:249], v[118:121], v[30:33]
	v_mfma_f32_16x16x32_bf16 v[34:37], v[234:237], v[122:125], v[34:37]
	v_mfma_f32_16x16x32_bf16 v[38:41], v[238:241], v[122:125], v[38:41]
	v_mfma_f32_16x16x32_bf16 v[42:45], v[242:245], v[122:125], v[42:45]
	v_mfma_f32_16x16x32_bf16 v[46:49], v[246:249], v[122:125], v[46:49]
	v_mfma_f32_16x16x32_bf16 v[50:53], v[234:237], v[126:129], v[50:53]
	v_mfma_f32_16x16x32_bf16 v[54:57], v[238:241], v[126:129], v[54:57]
	v_mfma_f32_16x16x32_bf16 v[58:61], v[242:245], v[126:129], v[58:61]
	v_mfma_f32_16x16x32_bf16 v[62:65], v[246:249], v[126:129], v[62:65]
	ds_read_b128 v[234:237], v214 offset:20480
	ds_read_b128 v[238:241], v214 offset:21504
	ds_read_b128 v[242:245], v214 offset:22528
	ds_read_b128 v[246:249], v214 offset:23552
	s_waitcnt lgkmcnt(4)
	v_mfma_f32_16x16x32_bf16 v[2:5], v[218:221], v[130:133], v[2:5]
	v_mfma_f32_16x16x32_bf16 v[6:9], v[222:225], v[130:133], v[6:9]
	v_mfma_f32_16x16x32_bf16 v[10:13], v[226:229], v[130:133], v[10:13]
	v_mfma_f32_16x16x32_bf16 v[14:17], v[230:233], v[130:133], v[14:17]
	v_mfma_f32_16x16x32_bf16 v[18:21], v[218:221], v[134:137], v[18:21]
	v_mfma_f32_16x16x32_bf16 v[22:25], v[222:225], v[134:137], v[22:25]
	v_mfma_f32_16x16x32_bf16 v[26:29], v[226:229], v[134:137], v[26:29]
	v_mfma_f32_16x16x32_bf16 v[30:33], v[230:233], v[134:137], v[30:33]
	v_mfma_f32_16x16x32_bf16 v[34:37], v[218:221], v[138:141], v[34:37]
	v_mfma_f32_16x16x32_bf16 v[38:41], v[222:225], v[138:141], v[38:41]
	v_mfma_f32_16x16x32_bf16 v[42:45], v[226:229], v[138:141], v[42:45]
	v_mfma_f32_16x16x32_bf16 v[46:49], v[230:233], v[138:141], v[46:49]
	v_mfma_f32_16x16x32_bf16 v[50:53], v[218:221], v[142:145], v[50:53]
	v_mfma_f32_16x16x32_bf16 v[54:57], v[222:225], v[142:145], v[54:57]
	v_mfma_f32_16x16x32_bf16 v[58:61], v[226:229], v[142:145], v[58:61]
	v_mfma_f32_16x16x32_bf16 v[62:65], v[230:233], v[142:145], v[62:65]
	ds_read_b128 v[218:221], v214 offset:24576
	ds_read_b128 v[222:225], v214 offset:25600
	ds_read_b128 v[226:229], v214 offset:26624
	ds_read_b128 v[230:233], v214 offset:27648
	s_waitcnt lgkmcnt(4)
	v_mfma_f32_16x16x32_bf16 v[2:5], v[234:237], v[146:149], v[2:5]
	v_mfma_f32_16x16x32_bf16 v[6:9], v[238:241], v[146:149], v[6:9]
	v_mfma_f32_16x16x32_bf16 v[10:13], v[242:245], v[146:149], v[10:13]
	v_mfma_f32_16x16x32_bf16 v[14:17], v[246:249], v[146:149], v[14:17]
	v_mfma_f32_16x16x32_bf16 v[18:21], v[234:237], v[150:153], v[18:21]
	v_mfma_f32_16x16x32_bf16 v[22:25], v[238:241], v[150:153], v[22:25]
	v_mfma_f32_16x16x32_bf16 v[26:29], v[242:245], v[150:153], v[26:29]
	v_mfma_f32_16x16x32_bf16 v[30:33], v[246:249], v[150:153], v[30:33]
	v_mfma_f32_16x16x32_bf16 v[34:37], v[234:237], v[154:157], v[34:37]
	v_mfma_f32_16x16x32_bf16 v[38:41], v[238:241], v[154:157], v[38:41]
	v_mfma_f32_16x16x32_bf16 v[42:45], v[242:245], v[154:157], v[42:45]
	v_mfma_f32_16x16x32_bf16 v[46:49], v[246:249], v[154:157], v[46:49]
	v_mfma_f32_16x16x32_bf16 v[50:53], v[234:237], v[158:161], v[50:53]
	v_mfma_f32_16x16x32_bf16 v[54:57], v[238:241], v[158:161], v[54:57]
	v_mfma_f32_16x16x32_bf16 v[58:61], v[242:245], v[158:161], v[58:61]
	v_mfma_f32_16x16x32_bf16 v[62:65], v[246:249], v[158:161], v[62:65]
	ds_read_b128 v[234:237], v214 offset:28672
	ds_read_b128 v[238:241], v214 offset:29696
	ds_read_b128 v[242:245], v214 offset:30720
	ds_read_b128 v[246:249], v214 offset:31744
	s_waitcnt lgkmcnt(4)
	v_mfma_f32_16x16x32_bf16 v[2:5], v[218:221], v[162:165], v[2:5]
	v_mfma_f32_16x16x32_bf16 v[6:9], v[222:225], v[162:165], v[6:9]
	v_mfma_f32_16x16x32_bf16 v[10:13], v[226:229], v[162:165], v[10:13]
	v_mfma_f32_16x16x32_bf16 v[14:17], v[230:233], v[162:165], v[14:17]
	v_mfma_f32_16x16x32_bf16 v[18:21], v[218:221], v[166:169], v[18:21]
	v_mfma_f32_16x16x32_bf16 v[22:25], v[222:225], v[166:169], v[22:25]
	v_mfma_f32_16x16x32_bf16 v[26:29], v[226:229], v[166:169], v[26:29]
	v_mfma_f32_16x16x32_bf16 v[30:33], v[230:233], v[166:169], v[30:33]
	v_mfma_f32_16x16x32_bf16 v[34:37], v[218:221], v[170:173], v[34:37]
	v_mfma_f32_16x16x32_bf16 v[38:41], v[222:225], v[170:173], v[38:41]
	v_mfma_f32_16x16x32_bf16 v[42:45], v[226:229], v[170:173], v[42:45]
	v_mfma_f32_16x16x32_bf16 v[46:49], v[230:233], v[170:173], v[46:49]
	v_mfma_f32_16x16x32_bf16 v[50:53], v[218:221], v[174:177], v[50:53]
	v_mfma_f32_16x16x32_bf16 v[54:57], v[222:225], v[174:177], v[54:57]
	v_mfma_f32_16x16x32_bf16 v[58:61], v[226:229], v[174:177], v[58:61]
	v_mfma_f32_16x16x32_bf16 v[62:65], v[230:233], v[174:177], v[62:65]
	s_waitcnt lgkmcnt(0)
	v_mfma_f32_16x16x32_bf16 v[2:5], v[234:237], v[178:181], v[2:5]
	v_mfma_f32_16x16x32_bf16 v[6:9], v[238:241], v[178:181], v[6:9]
	v_mfma_f32_16x16x32_bf16 v[10:13], v[242:245], v[178:181], v[10:13]
	v_mfma_f32_16x16x32_bf16 v[14:17], v[246:249], v[178:181], v[14:17]
	v_mfma_f32_16x16x32_bf16 v[18:21], v[234:237], v[182:185], v[18:21]
	v_mfma_f32_16x16x32_bf16 v[22:25], v[238:241], v[182:185], v[22:25]
	v_mfma_f32_16x16x32_bf16 v[26:29], v[242:245], v[182:185], v[26:29]
	v_mfma_f32_16x16x32_bf16 v[30:33], v[246:249], v[182:185], v[30:33]
	v_mfma_f32_16x16x32_bf16 v[34:37], v[234:237], v[186:189], v[34:37]
	v_mfma_f32_16x16x32_bf16 v[38:41], v[238:241], v[186:189], v[38:41]
	v_mfma_f32_16x16x32_bf16 v[42:45], v[242:245], v[186:189], v[42:45]
	v_mfma_f32_16x16x32_bf16 v[46:49], v[246:249], v[186:189], v[46:49]
	v_mfma_f32_16x16x32_bf16 v[50:53], v[234:237], v[190:193], v[50:53]
	v_mfma_f32_16x16x32_bf16 v[54:57], v[238:241], v[190:193], v[54:57]
	v_mfma_f32_16x16x32_bf16 v[58:61], v[242:245], v[190:193], v[58:61]
	v_mfma_f32_16x16x32_bf16 v[62:65], v[246:249], v[190:193], v[62:65]
	s_nop 7
	s_barrier
	ds_write_b128 v206, v[2:5] offset:0
	ds_write_b128 v206, v[6:9] offset:1024
	ds_write_b128 v206, v[10:13] offset:2048
	ds_write_b128 v206, v[14:17] offset:3072
	ds_write_b128 v206, v[18:21] offset:4096
	ds_write_b128 v206, v[22:25] offset:5120
	ds_write_b128 v206, v[26:29] offset:6144
	ds_write_b128 v206, v[30:33] offset:7168
	ds_write_b128 v206, v[34:37] offset:8192
	ds_write_b128 v206, v[38:41] offset:9216
	ds_write_b128 v206, v[42:45] offset:10240
	ds_write_b128 v206, v[46:49] offset:11264
	ds_write_b128 v206, v[50:53] offset:12288
	ds_write_b128 v206, v[54:57] offset:13312
	ds_write_b128 v206, v[58:61] offset:14336
	ds_write_b128 v206, v[62:65] offset:15360
	s_waitcnt lgkmcnt(0)
	s_barrier
	ds_read_b128 v[2:5], v207 offset:0
	ds_read_b128 v[6:9], v207 offset:16384
	ds_read_b128 v[10:13], v207 offset:32768
	ds_read_b128 v[14:17], v207 offset:49152
	ds_read_b128 v[18:21], v207 offset:1024
	ds_read_b128 v[22:25], v207 offset:17408
	ds_read_b128 v[26:29], v207 offset:33792
	ds_read_b128 v[30:33], v207 offset:50176
	ds_read_b128 v[34:37], v207 offset:2048
	ds_read_b128 v[38:41], v207 offset:18432
	ds_read_b128 v[42:45], v207 offset:34816
	ds_read_b128 v[46:49], v207 offset:51200
	ds_read_b128 v[50:53], v207 offset:3072
	ds_read_b128 v[54:57], v207 offset:19456
	ds_read_b128 v[58:61], v207 offset:35840
	ds_read_b128 v[62:65], v207 offset:52224
	s_waitcnt lgkmcnt(12)
	v_add_f32_e32 v2, v2, v6
	v_add_f32_e32 v3, v3, v7
	v_add_f32_e32 v4, v4, v8
	v_add_f32_e32 v5, v5, v9
	v_add_f32_e32 v10, v10, v14
	v_add_f32_e32 v11, v11, v15
	v_add_f32_e32 v12, v12, v16
	v_add_f32_e32 v13, v13, v17
	v_add_f32_e32 v2, v2, v10
	v_add_f32_e32 v3, v3, v11
	v_add_f32_e32 v4, v4, v12
	v_add_f32_e32 v5, v5, v13
	s_waitcnt lgkmcnt(8)
	v_add_f32_e32 v18, v18, v22
	v_add_f32_e32 v19, v19, v23
	v_add_f32_e32 v20, v20, v24
	v_add_f32_e32 v21, v21, v25
	v_add_f32_e32 v26, v26, v30
	v_add_f32_e32 v27, v27, v31
	v_add_f32_e32 v28, v28, v32
	v_add_f32_e32 v29, v29, v33
	v_add_f32_e32 v18, v18, v26
	v_add_f32_e32 v19, v19, v27
	v_add_f32_e32 v20, v20, v28
	v_add_f32_e32 v21, v21, v29
	s_waitcnt lgkmcnt(4)
	v_add_f32_e32 v34, v34, v38
	v_add_f32_e32 v35, v35, v39
	v_add_f32_e32 v36, v36, v40
	v_add_f32_e32 v37, v37, v41
	v_add_f32_e32 v42, v42, v46
	v_add_f32_e32 v43, v43, v47
	v_add_f32_e32 v44, v44, v48
	v_add_f32_e32 v45, v45, v49
	v_add_f32_e32 v34, v34, v42
	v_add_f32_e32 v35, v35, v43
	v_add_f32_e32 v36, v36, v44
	v_add_f32_e32 v37, v37, v45
	s_waitcnt lgkmcnt(0)
	v_add_f32_e32 v50, v50, v54
	v_add_f32_e32 v51, v51, v55
	v_add_f32_e32 v52, v52, v56
	v_add_f32_e32 v53, v53, v57
	v_add_f32_e32 v58, v58, v62
	v_add_f32_e32 v59, v59, v63
	v_add_f32_e32 v60, v60, v64
	v_add_f32_e32 v61, v61, v65
	v_add_f32_e32 v50, v50, v58
	v_add_f32_e32 v51, v51, v59
	v_add_f32_e32 v52, v52, v60
	v_add_f32_e32 v53, v53, v61
	v_max_f32_e32 v2, 0, v2
	v_max_f32_e32 v3, 0, v3
	v_max_f32_e32 v4, 0, v4
	v_max_f32_e32 v5, 0, v5
	v_mul_f32_e32 v2, v2, v2
	v_mul_f32_e32 v3, v3, v3
	v_mul_f32_e32 v4, v4, v4
	v_mul_f32_e32 v5, v5, v5
	v_cvt_pk_bf16_f32 v210, v2, v3
	v_cvt_pk_bf16_f32 v211, v4, v5
	global_store_dwordx2 v209, v[210:211], s[24:25] offset:0
	v_max_f32_e32 v18, 0, v18
	v_max_f32_e32 v19, 0, v19
	v_max_f32_e32 v20, 0, v20
	v_max_f32_e32 v21, 0, v21
	v_mul_f32_e32 v18, v18, v18
	v_mul_f32_e32 v19, v19, v19
	v_mul_f32_e32 v20, v20, v20
	v_mul_f32_e32 v21, v21, v21
	v_cvt_pk_bf16_f32 v212, v18, v19
	v_cvt_pk_bf16_f32 v213, v20, v21
	global_store_dwordx2 v209, v[212:213], s[24:25] offset:32
	v_max_f32_e32 v34, 0, v34
	v_max_f32_e32 v35, 0, v35
	v_max_f32_e32 v36, 0, v36
	v_max_f32_e32 v37, 0, v37
	v_mul_f32_e32 v34, v34, v34
	v_mul_f32_e32 v35, v35, v35
	v_mul_f32_e32 v36, v36, v36
	v_mul_f32_e32 v37, v37, v37
	v_cvt_pk_bf16_f32 v214, v34, v35
	v_cvt_pk_bf16_f32 v215, v36, v37
	global_store_dwordx2 v209, v[214:215], s[24:25] offset:64
	v_max_f32_e32 v50, 0, v50
	v_max_f32_e32 v51, 0, v51
	v_max_f32_e32 v52, 0, v52
	v_max_f32_e32 v53, 0, v53
	v_mul_f32_e32 v50, v50, v50
	v_mul_f32_e32 v51, v51, v51
	v_mul_f32_e32 v52, v52, v52
	v_mul_f32_e32 v53, v53, v53
	v_cvt_pk_bf16_f32 v216, v50, v51
	v_cvt_pk_bf16_f32 v217, v52, v53
	global_store_dwordx2 v209, v[216:217], s[24:25] offset:96
	s_barrier
	s_add_i32 s12, s12, s3
	s_cmpk_lt_u32 s12, 0x100
	s_cbranch_scc1 .Lsmp5_unit

	.amdhsa_kernel _Z10fwd_kernelILi5ELi6EEv4Args
		.amdhsa_group_segment_fixed_size 0
		.amdhsa_private_segment_fixed_size 0
		.amdhsa_kernarg_size 488
		.amdhsa_user_sgpr_count 2
		.amdhsa_user_sgpr_dispatch_ptr 0
		.amdhsa_user_sgpr_queue_ptr 0
		.amdhsa_user_sgpr_kernarg_segment_ptr 1
		.amdhsa_user_sgpr_dispatch_id 0
		.amdhsa_user_sgpr_kernarg_preload_length 0
		.amdhsa_user_sgpr_kernarg_preload_offset 0
		.amdhsa_user_sgpr_private_segment_size 0
		.amdhsa_uses_dynamic_stack 0
		.amdhsa_enable_private_segment 0
		.amdhsa_system_sgpr_workgroup_id_x 1
		.amdhsa_system_sgpr_workgroup_id_y 0
		.amdhsa_system_sgpr_workgroup_id_z 0
		.amdhsa_system_sgpr_workgroup_info 0
		.amdhsa_system_vgpr_workitem_id 0
		.amdhsa_next_free_vgpr 256
		.amdhsa_next_free_sgpr 62
		.amdhsa_accum_offset 256
		.amdhsa_reserve_vcc 1
		.amdhsa_float_round_mode_32 0
		.amdhsa_float_round_mode_16_64 0
		.amdhsa_float_denorm_mode_32 3
		.amdhsa_float_denorm_mode_16_64 3
		.amdhsa_dx10_clamp 1
		.amdhsa_ieee_mode 1
		.amdhsa_fp16_overflow 0
		.amdhsa_tg_split 0
		.amdhsa_exception_fp_ieee_invalid_op 0
		.amdhsa_exception_fp_denorm_src 0
		.amdhsa_exception_fp_ieee_div_zero 0
		.amdhsa_exception_fp_ieee_overflow 0
		.amdhsa_exception_fp_ieee_underflow 0
		.amdhsa_exception_fp_ieee_inexact 0
		.amdhsa_exception_int_div_zero 0
	.end_amdhsa_kernel

.Linp8_unit:
	s_lshr_b32 s29, s12, 3
	s_cmp_gt_u32 s29, 23
	s_cbranch_scc1 .Linp8_next
	s_add_u32 s20, s16, 0x5100000
	s_addc_u32 s21, s17, 0
	s_add_u32 s22, s16, 0x1900000
	s_addc_u32 s23, s17, 0
	s_add_u32 s24, s16, 0xd400000
	s_addc_u32 s25, s17, 0
	s_and_b32 s28, s12, 7
	s_lshl_b32 s29, s29, 1
	s_add_u32 s29, s29, s6
	s_lshr_b32 s30, s29, 3
	s_mul_i32 s28, s28, 6
	s_add_u32 s30, s30, s28
	s_and_b32 s31, s29, 7
	s_lshl_b32 s33, s31, 17
	s_lshl_b32 s34, s30, 17
	v_lshlrev_b32_e32 v215, 11, v202
	v_lshl_add_u32 v215, v203, 4, v215
	v_add_u32_e32 v194, s33, v204
	v_add_u32_e32 v198, s34, v215
	v_add_u32_e32 v195, s33, v204
	v_add_u32_e32 v199, s34, v215
	v_add_u32_e32 v196, s33, v204
	v_add_u32_e32 v200, s34, v215
	v_add_u32_e32 v197, s33, v204
	v_add_u32_e32 v201, s34, v215
	v_add_u32_e32 v195, 0x8000, v195
	v_add_u32_e32 v199, 0x8000, v199
	v_add_u32_e32 v196, 0x10000, v196
	v_add_u32_e32 v200, 0x10000, v200
	v_add_u32_e32 v197, 0x18000, v197
	v_add_u32_e32 v201, 0x18000, v201
	s_mul_i32 s33, s31, 0x60000
	s_lshl_b32 s34, s30, 7
	s_add_u32 s33, s33, s34
	v_add_u32_e32 v211, s33, v209
	s_lshr_b32 s35, s30, 4
	s_and_b32 s36, s30, 15
	s_lshl_b32 s36, s36, 8
	s_mov_b32 s37, 0x3f800000
	s_mov_b32 s42, 1
	s_cmp_eq_u32 s35, 0
	s_cselect_b32 s37, 0x3e38aa3b, s37
	s_cselect_b32 s42, 0, s42
	s_sub_u32 s43, s35, 1
	s_lshl_b32 s43, s43, 24
	s_lshl_b32 s44, s31, 21
	s_add_u32 s43, s43, s44
	s_add_u32 s43, s43, s36
	s_add_u32 s38, s40, s43
	s_addc_u32 s39, s41, 0
	s_add_u32 s38, s38, 0xd844000
	s_addc_u32 s39, s39, 0
	s_lshl_b32 s44, s4, 8
	s_add_u32 s44, s22, s44
	s_addc_u32 s45, s23, 0
	s_lshl_b32 s46, s4, 14
	s_add_i32 m0, s46, 0x0
	global_load_dwordx4 v[66:69], v194, s[20:21] offset:0
	global_load_dwordx4 v[70:73], v195, s[20:21] offset:0
	global_load_lds_dwordx4 v198, s[44:45]
	s_add_i32 m0, s46, 0x400
	global_load_dwordx4 v[74:77], v196, s[20:21] offset:0
	global_load_dwordx4 v[78:81], v197, s[20:21] offset:0
	global_load_lds_dwordx4 v199, s[44:45]
	s_add_i32 m0, s46, 0x800
	global_load_dwordx4 v[82:85], v194, s[20:21] offset:64
	global_load_dwordx4 v[86:89], v195, s[20:21] offset:64
	global_load_lds_dwordx4 v200, s[44:45]
	s_add_i32 m0, s46, 0xc00
	global_load_dwordx4 v[90:93], v196, s[20:21] offset:64
	global_load_dwordx4 v[94:97], v197, s[20:21] offset:64
	global_load_lds_dwordx4 v201, s[44:45]
	s_add_u32 s44, s44, 64
	s_addc_u32 s45, s45, 0
	s_add_i32 m0, s46, 0x1000
	global_load_dwordx4 v[98:101], v194, s[20:21] offset:128
	global_load_dwordx4 v[102:105], v195, s[20:21] offset:128
	global_load_lds_dwordx4 v198, s[44:45]
	s_add_i32 m0, s46, 0x1400
	global_load_dwordx4 v[106:109], v196, s[20:21] offset:128
	global_load_dwordx4 v[110:113], v197, s[20:21] offset:128
	global_load_lds_dwordx4 v199, s[44:45]
	s_add_i32 m0, s46, 0x1800
	global_load_dwordx4 v[114:117], v194, s[20:21] offset:192
	global_load_dwordx4 v[118:121], v195, s[20:21] offset:192
	global_load_lds_dwordx4 v200, s[44:45]
	s_add_i32 m0, s46, 0x1c00
	global_load_dwordx4 v[122:125], v196, s[20:21] offset:192
	global_load_dwordx4 v[126:129], v197, s[20:21] offset:192
	global_load_lds_dwordx4 v201, s[44:45]
	s_add_u32 s44, s44, 64
	s_addc_u32 s45, s45, 0
	s_add_i32 m0, s46, 0x2000
	global_load_dwordx4 v[130:133], v194, s[20:21] offset:256
	global_load_dwordx4 v[134:137], v195, s[20:21] offset:256
	global_load_lds_dwordx4 v198, s[44:45]
	s_add_i32 m0, s46, 0x2400
	global_load_dwordx4 v[138:141], v196, s[20:21] offset:256
	global_load_dwordx4 v[142:145], v197, s[20:21] offset:256
	global_load_lds_dwordx4 v199, s[44:45]
	s_add_i32 m0, s46, 0x2800
	global_load_dwordx4 v[146:149], v194, s[20:21] offset:320
	global_load_dwordx4 v[150:153], v195, s[20:21] offset:320
	global_load_lds_dwordx4 v200, s[44:45]
	s_add_i32 m0, s46, 0x2c00
	global_load_dwordx4 v[154:157], v196, s[20:21] offset:320
	global_load_dwordx4 v[158:161], v197, s[20:21] offset:320
	global_load_lds_dwordx4 v201, s[44:45]
	s_add_u32 s44, s44, 64
	s_addc_u32 s45, s45, 0
	s_add_i32 m0, s46, 0x3000
	global_load_dwordx4 v[162:165], v194, s[20:21] offset:384
	global_load_dwordx4 v[166:169], v195, s[20:21] offset:384
	global_load_lds_dwordx4 v198, s[44:45]
	s_add_i32 m0, s46, 0x3400
	global_load_dwordx4 v[170:173], v196, s[20:21] offset:384
	global_load_dwordx4 v[174:177], v197, s[20:21] offset:384
	global_load_lds_dwordx4 v199, s[44:45]
	s_add_i32 m0, s46, 0x3800
	global_load_dwordx4 v[178:181], v194, s[20:21] offset:448
	global_load_dwordx4 v[182:185], v195, s[20:21] offset:448
	global_load_lds_dwordx4 v200, s[44:45]
	s_add_i32 m0, s46, 0x3c00
	global_load_dwordx4 v[186:189], v196, s[20:21] offset:448
	global_load_dwordx4 v[190:193], v197, s[20:21] offset:448
	global_load_lds_dwordx4 v201, s[44:45]
	s_waitcnt vmcnt(0)
	s_barrier
	s_lshl_b32 s47, s5, 15
	v_lshl_add_u32 v214, v205, 4, s47
	ds_read_b128 v[218:221], v214 offset:0
	ds_read_b128 v[222:225], v214 offset:1024
	ds_read_b128 v[226:229], v214 offset:2048
	ds_read_b128 v[230:233], v214 offset:3072
	ds_read_b128 v[234:237], v214 offset:4096
	ds_read_b128 v[238:241], v214 offset:5120
	ds_read_b128 v[242:245], v214 offset:6144
	ds_read_b128 v[246:249], v214 offset:7168
	s_waitcnt lgkmcnt(4)
	v_mfma_f32_16x16x32_bf16 v[2:5], v[218:221], v[66:69], 0
	v_mfma_f32_16x16x32_bf16 v[6:9], v[222:225], v[66:69], 0
	v_mfma_f32_16x16x32_bf16 v[10:13], v[226:229], v[66:69], 0
	v_mfma_f32_16x16x32_bf16 v[14:17], v[230:233], v[66:69], 0
	v_mfma_f32_16x16x32_bf16 v[18:21], v[218:221], v[70:73], 0
	v_mfma_f32_16x16x32_bf16 v[22:25], v[222:225], v[70:73], 0
	v_mfma_f32_16x16x32_bf16 v[26:29], v[226:229], v[70:73], 0
	v_mfma_f32_16x16x32_bf16 v[30:33], v[230:233], v[70:73], 0
	v_mfma_f32_16x16x32_bf16 v[34:37], v[218:221], v[74:77], 0
	v_mfma_f32_16x16x32_bf16 v[38:41], v[222:225], v[74:77], 0
	v_mfma_f32_16x16x32_bf16 v[42:45], v[226:229], v[74:77], 0
	v_mfma_f32_16x16x32_bf16 v[46:49], v[230:233], v[74:77], 0
	v_mfma_f32_16x16x32_bf16 v[50:53], v[218:221], v[78:81], 0
	v_mfma_f32_16x16x32_bf16 v[54:57], v[222:225], v[78:81], 0
	v_mfma_f32_16x16x32_bf16 v[58:61], v[226:229], v[78:81], 0
	v_mfma_f32_16x16x32_bf16 v[62:65], v[230:233], v[78:81], 0
	ds_read_b128 v[218:221], v214 offset:8192
	ds_read_b128 v[222:225], v214 offset:9216
	ds_read_b128 v[226:229], v214 offset:10240
	ds_read_b128 v[230:233], v214 offset:11264
	s_waitcnt lgkmcnt(4)
	v_mfma_f32_16x16x32_bf16 v[2:5], v[234:237], v[82:85], v[2:5]
	v_mfma_f32_16x16x32_bf16 v[6:9], v[238:241], v[82:85], v[6:9]
	v_mfma_f32_16x16x32_bf16 v[10:13], v[242:245], v[82:85], v[10:13]
	v_mfma_f32_16x16x32_bf16 v[14:17], v[246:249], v[82:85], v[14:17]
	v_mfma_f32_16x16x32_bf16 v[18:21], v[234:237], v[86:89], v[18:21]
	v_mfma_f32_16x16x32_bf16 v[22:25], v[238:241], v[86:89], v[22:25]
	v_mfma_f32_16x16x32_bf16 v[26:29], v[242:245], v[86:89], v[26:29]
	v_mfma_f32_16x16x32_bf16 v[30:33], v[246:249], v[86:89], v[30:33]
	v_mfma_f32_16x16x32_bf16 v[34:37], v[234:237], v[90:93], v[34:37]
	v_mfma_f32_16x16x32_bf16 v[38:41], v[238:241], v[90:93], v[38:41]
	v_mfma_f32_16x16x32_bf16 v[42:45], v[242:245], v[90:93], v[42:45]
	v_mfma_f32_16x16x32_bf16 v[46:49], v[246:249], v[90:93], v[46:49]
	v_mfma_f32_16x16x32_bf16 v[50:53], v[234:237], v[94:97], v[50:53]
	v_mfma_f32_16x16x32_bf16 v[54:57], v[238:241], v[94:97], v[54:57]
	v_mfma_f32_16x16x32_bf16 v[58:61], v[242:245], v[94:97], v[58:61]
	v_mfma_f32_16x16x32_bf16 v[62:65], v[246:249], v[94:97], v[62:65]
	ds_read_b128 v[234:237], v214 offset:12288
	ds_read_b128 v[238:241], v214 offset:13312
	ds_read_b128 v[242:245], v214 offset:14336
	ds_read_b128 v[246:249], v214 offset:15360
	s_waitcnt lgkmcnt(4)
	v_mfma_f32_16x16x32_bf16 v[2:5], v[218:221], v[98:101], v[2:5]
	v_mfma_f32_16x16x32_bf16 v[6:9], v[222:225], v[98:101], v[6:9]
	v_mfma_f32_16x16x32_bf16 v[10:13], v[226:229], v[98:101], v[10:13]
	v_mfma_f32_16x16x32_bf16 v[14:17], v[230:233], v[98:101], v[14:17]
	v_mfma_f32_16x16x32_bf16 v[18:21], v[218:221], v[102:105], v[18:21]
	v_mfma_f32_16x16x32_bf16 v[22:25], v[222:225], v[102:105], v[22:25]
	v_mfma_f32_16x16x32_bf16 v[26:29], v[226:229], v[102:105], v[26:29]
	v_mfma_f32_16x16x32_bf16 v[30:33], v[230:233], v[102:105], v[30:33]
	v_mfma_f32_16x16x32_bf16 v[34:37], v[218:221], v[106:109], v[34:37]
	v_mfma_f32_16x16x32_bf16 v[38:41], v[222:225], v[106:109], v[38:41]
	v_mfma_f32_16x16x32_bf16 v[42:45], v[226:229], v[106:109], v[42:45]
	v_mfma_f32_16x16x32_bf16 v[46:49], v[230:233], v[106:109], v[46:49]
	v_mfma_f32_16x16x32_bf16 v[50:53], v[218:221], v[110:113], v[50:53]
	v_mfma_f32_16x16x32_bf16 v[54:57], v[222:225], v[110:113], v[54:57]
	v_mfma_f32_16x16x32_bf16 v[58:61], v[226:229], v[110:113], v[58:61]
	v_mfma_f32_16x16x32_bf16 v[62:65], v[230:233], v[110:113], v[62:65]
	ds_read_b128 v[218:221], v214 offset:16384
	ds_read_b128 v[222:225], v214 offset:17408
	ds_read_b128 v[226:229], v214 offset:18432
	ds_read_b128 v[230:233], v214 offset:19456
	s_waitcnt lgkmcnt(4)
	v_mfma_f32_16x16x32_bf16 v[2:5], v[234:237], v[114:117], v[2:5]
	v_mfma_f32_16x16x32_bf16 v[6:9], v[238:241], v[114:117], v[6:9]
	v_mfma_f32_16x16x32_bf16 v[10:13], v[242:245], v[114:117], v[10:13]
	v_mfma_f32_16x16x32_bf16 v[14:17], v[246:249], v[114:117], v[14:17]
	v_mfma_f32_16x16x32_bf16 v[18:21], v[234:237], v[118:121], v[18:21]
	v_mfma_f32_16x16x32_bf16 v[22:25], v[238:241], v[118:121], v[22:25]
	v_mfma_f32_16x16x32_bf16 v[26:29], v[242:245], v[118:121], v[26:29]
	v_mfma_f32_16x16x32_bf16 v[30:33], v[246:249], v[118:121], v[30:33]
	v_mfma_f32_16x16x32_bf16 v[34:37], v[234:237], v[122:125], v[34:37]
	v_mfma_f32_16x16x32_bf16 v[38:41], v[238:241], v[122:125], v[38:41]
	v_mfma_f32_16x16x32_bf16 v[42:45], v[242:245], v[122:125], v[42:45]
	v_mfma_f32_16x16x32_bf16 v[46:49], v[246:249], v[122:125], v[46:49]
	v_mfma_f32_16x16x32_bf16 v[50:53], v[234:237], v[126:129], v[50:53]
	v_mfma_f32_16x16x32_bf16 v[54:57], v[238:241], v[126:129], v[54:57]
	v_mfma_f32_16x16x32_bf16 v[58:61], v[242:245], v[126:129], v[58:61]
	v_mfma_f32_16x16x32_bf16 v[62:65], v[246:249], v[126:129], v[62:65]
	ds_read_b128 v[234:237], v214 offset:20480
	ds_read_b128 v[238:241], v214 offset:21504
	ds_read_b128 v[242:245], v214 offset:22528
	ds_read_b128 v[246:249], v214 offset:23552
	s_waitcnt lgkmcnt(4)
	v_mfma_f32_16x16x32_bf16 v[2:5], v[218:221], v[130:133], v[2:5]
	v_mfma_f32_16x16x32_bf16 v[6:9], v[222:225], v[130:133], v[6:9]
	v_mfma_f32_16x16x32_bf16 v[10:13], v[226:229], v[130:133], v[10:13]
	v_mfma_f32_16x16x32_bf16 v[14:17], v[230:233], v[130:133], v[14:17]
	v_mfma_f32_16x16x32_bf16 v[18:21], v[218:221], v[134:137], v[18:21]
	v_mfma_f32_16x16x32_bf16 v[22:25], v[222:225], v[134:137], v[22:25]
	v_mfma_f32_16x16x32_bf16 v[26:29], v[226:229], v[134:137], v[26:29]
	v_mfma_f32_16x16x32_bf16 v[30:33], v[230:233], v[134:137], v[30:33]
	v_mfma_f32_16x16x32_bf16 v[34:37], v[218:221], v[138:141], v[34:37]
	v_mfma_f32_16x16x32_bf16 v[38:41], v[222:225], v[138:141], v[38:41]
	v_mfma_f32_16x16x32_bf16 v[42:45], v[226:229], v[138:141], v[42:45]
	v_mfma_f32_16x16x32_bf16 v[46:49], v[230:233], v[138:141], v[46:49]
	v_mfma_f32_16x16x32_bf16 v[50:53], v[218:221], v[142:145], v[50:53]
	v_mfma_f32_16x16x32_bf16 v[54:57], v[222:225], v[142:145], v[54:57]
	v_mfma_f32_16x16x32_bf16 v[58:61], v[226:229], v[142:145], v[58:61]
	v_mfma_f32_16x16x32_bf16 v[62:65], v[230:233], v[142:145], v[62:65]
	ds_read_b128 v[218:221], v214 offset:24576
	ds_read_b128 v[222:225], v214 offset:25600
	ds_read_b128 v[226:229], v214 offset:26624
	ds_read_b128 v[230:233], v214 offset:27648
	s_waitcnt lgkmcnt(4)
	v_mfma_f32_16x16x32_bf16 v[2:5], v[234:237], v[146:149], v[2:5]
	v_mfma_f32_16x16x32_bf16 v[6:9], v[238:241], v[146:149], v[6:9]
	v_mfma_f32_16x16x32_bf16 v[10:13], v[242:245], v[146:149], v[10:13]
	v_mfma_f32_16x16x32_bf16 v[14:17], v[246:249], v[146:149], v[14:17]
	v_mfma_f32_16x16x32_bf16 v[18:21], v[234:237], v[150:153], v[18:21]
	v_mfma_f32_16x16x32_bf16 v[22:25], v[238:241], v[150:153], v[22:25]
	v_mfma_f32_16x16x32_bf16 v[26:29], v[242:245], v[150:153], v[26:29]
	v_mfma_f32_16x16x32_bf16 v[30:33], v[246:249], v[150:153], v[30:33]
	v_mfma_f32_16x16x32_bf16 v[34:37], v[234:237], v[154:157], v[34:37]
	v_mfma_f32_16x16x32_bf16 v[38:41], v[238:241], v[154:157], v[38:41]
	v_mfma_f32_16x16x32_bf16 v[42:45], v[242:245], v[154:157], v[42:45]
	v_mfma_f32_16x16x32_bf16 v[46:49], v[246:249], v[154:157], v[46:49]
	v_mfma_f32_16x16x32_bf16 v[50:53], v[234:237], v[158:161], v[50:53]
	v_mfma_f32_16x16x32_bf16 v[54:57], v[238:241], v[158:161], v[54:57]
	v_mfma_f32_16x16x32_bf16 v[58:61], v[242:245], v[158:161], v[58:61]
	v_mfma_f32_16x16x32_bf16 v[62:65], v[246:249], v[158:161], v[62:65]
	ds_read_b128 v[234:237], v214 offset:28672
	ds_read_b128 v[238:241], v214 offset:29696
	ds_read_b128 v[242:245], v214 offset:30720
	ds_read_b128 v[246:249], v214 offset:31744
	s_waitcnt lgkmcnt(4)
	v_mfma_f32_16x16x32_bf16 v[2:5], v[218:221], v[162:165], v[2:5]
	v_mfma_f32_16x16x32_bf16 v[6:9], v[222:225], v[162:165], v[6:9]
	v_mfma_f32_16x16x32_bf16 v[10:13], v[226:229], v[162:165], v[10:13]
	v_mfma_f32_16x16x32_bf16 v[14:17], v[230:233], v[162:165], v[14:17]
	v_mfma_f32_16x16x32_bf16 v[18:21], v[218:221], v[166:169], v[18:21]
	v_mfma_f32_16x16x32_bf16 v[22:25], v[222:225], v[166:169], v[22:25]
	v_mfma_f32_16x16x32_bf16 v[26:29], v[226:229], v[166:169], v[26:29]
	v_mfma_f32_16x16x32_bf16 v[30:33], v[230:233], v[166:169], v[30:33]
	v_mfma_f32_16x16x32_bf16 v[34:37], v[218:221], v[170:173], v[34:37]
	v_mfma_f32_16x16x32_bf16 v[38:41], v[222:225], v[170:173], v[38:41]
	v_mfma_f32_16x16x32_bf16 v[42:45], v[226:229], v[170:173], v[42:45]
	v_mfma_f32_16x16x32_bf16 v[46:49], v[230:233], v[170:173], v[46:49]
	v_mfma_f32_16x16x32_bf16 v[50:53], v[218:221], v[174:177], v[50:53]
	v_mfma_f32_16x16x32_bf16 v[54:57], v[222:225], v[174:177], v[54:57]
	v_mfma_f32_16x16x32_bf16 v[58:61], v[226:229], v[174:177], v[58:61]
	v_mfma_f32_16x16x32_bf16 v[62:65], v[230:233], v[174:177], v[62:65]
	s_waitcnt lgkmcnt(0)
	v_mfma_f32_16x16x32_bf16 v[2:5], v[234:237], v[178:181], v[2:5]
	v_mfma_f32_16x16x32_bf16 v[6:9], v[238:241], v[178:181], v[6:9]
	v_mfma_f32_16x16x32_bf16 v[10:13], v[242:245], v[178:181], v[10:13]
	v_mfma_f32_16x16x32_bf16 v[14:17], v[246:249], v[178:181], v[14:17]
	v_mfma_f32_16x16x32_bf16 v[18:21], v[234:237], v[182:185], v[18:21]
	v_mfma_f32_16x16x32_bf16 v[22:25], v[238:241], v[182:185], v[22:25]
	v_mfma_f32_16x16x32_bf16 v[26:29], v[242:245], v[182:185], v[26:29]
	v_mfma_f32_16x16x32_bf16 v[30:33], v[246:249], v[182:185], v[30:33]
	v_mfma_f32_16x16x32_bf16 v[34:37], v[234:237], v[186:189], v[34:37]
	v_mfma_f32_16x16x32_bf16 v[38:41], v[238:241], v[186:189], v[38:41]
	v_mfma_f32_16x16x32_bf16 v[42:45], v[242:245], v[186:189], v[42:45]
	v_mfma_f32_16x16x32_bf16 v[46:49], v[246:249], v[186:189], v[46:49]
	v_mfma_f32_16x16x32_bf16 v[50:53], v[234:237], v[190:193], v[50:53]
	v_mfma_f32_16x16x32_bf16 v[54:57], v[238:241], v[190:193], v[54:57]
	v_mfma_f32_16x16x32_bf16 v[58:61], v[242:245], v[190:193], v[58:61]
	v_mfma_f32_16x16x32_bf16 v[62:65], v[246:249], v[190:193], v[62:65]
	s_nop 7
	s_barrier
	ds_write_b128 v206, v[2:5] offset:0
	ds_write_b128 v206, v[6:9] offset:1024
	ds_write_b128 v206, v[10:13] offset:2048
	ds_write_b128 v206, v[14:17] offset:3072
	ds_write_b128 v206, v[18:21] offset:4096
	ds_write_b128 v206, v[22:25] offset:5120
	ds_write_b128 v206, v[26:29] offset:6144
	ds_write_b128 v206, v[30:33] offset:7168
	ds_write_b128 v206, v[34:37] offset:8192
	ds_write_b128 v206, v[38:41] offset:9216
	ds_write_b128 v206, v[42:45] offset:10240
	ds_write_b128 v206, v[46:49] offset:11264
	ds_write_b128 v206, v[50:53] offset:12288
	ds_write_b128 v206, v[54:57] offset:13312
	ds_write_b128 v206, v[58:61] offset:14336
	ds_write_b128 v206, v[62:65] offset:15360
	s_waitcnt lgkmcnt(0)
	s_barrier
	ds_read_b128 v[2:5], v207 offset:0
	ds_read_b128 v[6:9], v207 offset:16384
	ds_read_b128 v[10:13], v207 offset:32768
	ds_read_b128 v[14:17], v207 offset:49152
	ds_read_b128 v[18:21], v207 offset:1024
	ds_read_b128 v[22:25], v207 offset:17408
	ds_read_b128 v[26:29], v207 offset:33792
	ds_read_b128 v[30:33], v207 offset:50176
	ds_read_b128 v[34:37], v207 offset:2048
	ds_read_b128 v[38:41], v207 offset:18432
	ds_read_b128 v[42:45], v207 offset:34816
	ds_read_b128 v[46:49], v207 offset:51200
	ds_read_b128 v[50:53], v207 offset:3072
	ds_read_b128 v[54:57], v207 offset:19456
	ds_read_b128 v[58:61], v207 offset:35840
	ds_read_b128 v[62:65], v207 offset:52224
	s_waitcnt lgkmcnt(12)
	v_add_f32_e32 v2, v2, v6
	v_add_f32_e32 v3, v3, v7
	v_add_f32_e32 v4, v4, v8
	v_add_f32_e32 v5, v5, v9
	v_add_f32_e32 v10, v10, v14
	v_add_f32_e32 v11, v11, v15
	v_add_f32_e32 v12, v12, v16
	v_add_f32_e32 v13, v13, v17
	v_add_f32_e32 v2, v2, v10
	v_add_f32_e32 v3, v3, v11
	v_add_f32_e32 v4, v4, v12
	v_add_f32_e32 v5, v5, v13
	s_waitcnt lgkmcnt(8)
	v_add_f32_e32 v18, v18, v22
	v_add_f32_e32 v19, v19, v23
	v_add_f32_e32 v20, v20, v24
	v_add_f32_e32 v21, v21, v25
	v_add_f32_e32 v26, v26, v30
	v_add_f32_e32 v27, v27, v31
	v_add_f32_e32 v28, v28, v32
	v_add_f32_e32 v29, v29, v33
	v_add_f32_e32 v18, v18, v26
	v_add_f32_e32 v19, v19, v27
	v_add_f32_e32 v20, v20, v28
	v_add_f32_e32 v21, v21, v29
	s_waitcnt lgkmcnt(4)
	v_add_f32_e32 v34, v34, v38
	v_add_f32_e32 v35, v35, v39
	v_add_f32_e32 v36, v36, v40
	v_add_f32_e32 v37, v37, v41
	v_add_f32_e32 v42, v42, v46
	v_add_f32_e32 v43, v43, v47
	v_add_f32_e32 v44, v44, v48
	v_add_f32_e32 v45, v45, v49
	v_add_f32_e32 v34, v34, v42
	v_add_f32_e32 v35, v35, v43
	v_add_f32_e32 v36, v36, v44
	v_add_f32_e32 v37, v37, v45
	s_waitcnt lgkmcnt(0)
	v_add_f32_e32 v50, v50, v54
	v_add_f32_e32 v51, v51, v55
	v_add_f32_e32 v52, v52, v56
	v_add_f32_e32 v53, v53, v57
	v_add_f32_e32 v58, v58, v62
	v_add_f32_e32 v59, v59, v63
	v_add_f32_e32 v60, v60, v64
	v_add_f32_e32 v61, v61, v65
	v_add_f32_e32 v50, v50, v58
	v_add_f32_e32 v51, v51, v59
	v_add_f32_e32 v52, v52, v60
	v_add_f32_e32 v53, v53, v61
	s_cmp_eq_u32 s42, 0
	s_cbranch_scc1 .Linp8_nof32
	global_store_dwordx4 v210, v[2:5], s[38:39] offset:0
	global_store_dwordx4 v210, v[18:21], s[38:39] offset:64
	global_store_dwordx4 v210, v[34:37], s[38:39] offset:128
	global_store_dwordx4 v210, v[50:53], s[38:39] offset:192
	s_nop 1

	.amdhsa_kernel _Z10fwd_kernelILi8ELi9EEv4Args
		.amdhsa_group_segment_fixed_size 0
		.amdhsa_private_segment_fixed_size 0
		.amdhsa_kernarg_size 488
		.amdhsa_user_sgpr_count 2
		.amdhsa_user_sgpr_dispatch_ptr 0
		.amdhsa_user_sgpr_queue_ptr 0
		.amdhsa_user_sgpr_kernarg_segment_ptr 1
		.amdhsa_user_sgpr_dispatch_id 0
		.amdhsa_user_sgpr_kernarg_preload_length 0
		.amdhsa_user_sgpr_kernarg_preload_offset 0
		.amdhsa_user_sgpr_private_segment_size 0
		.amdhsa_uses_dynamic_stack 0
		.amdhsa_enable_private_segment 0
		.amdhsa_system_sgpr_workgroup_id_x 1
		.amdhsa_system_sgpr_workgroup_id_y 0
		.amdhsa_system_sgpr_workgroup_id_z 0
		.amdhsa_system_sgpr_workgroup_info 0
		.amdhsa_system_vgpr_workitem_id 0
		.amdhsa_next_free_vgpr 256
		.amdhsa_next_free_sgpr 69
		.amdhsa_accum_offset 256
		.amdhsa_reserve_vcc 1
		.amdhsa_float_round_mode_32 0
		.amdhsa_float_round_mode_16_64 0
		.amdhsa_float_denorm_mode_32 3
		.amdhsa_float_denorm_mode_16_64 3
		.amdhsa_dx10_clamp 1
		.amdhsa_ieee_mode 1
		.amdhsa_fp16_overflow 0
		.amdhsa_tg_split 0
		.amdhsa_exception_fp_ieee_invalid_op 0
		.amdhsa_exception_fp_denorm_src 0
		.amdhsa_exception_fp_ieee_div_zero 0
		.amdhsa_exception_fp_ieee_overflow 0
		.amdhsa_exception_fp_ieee_underflow 0
		.amdhsa_exception_fp_ieee_inexact 0
		.amdhsa_exception_int_div_zero 0
	.end_amdhsa_kernel

.Lsmp12_unit:
	s_add_u32 s20, s16, 0x5100000
	s_addc_u32 s21, s17, 0
	s_add_u32 s22, s16, 0x2100000
	s_addc_u32 s23, s17, 0
	s_add_u32 s24, s16, 0xf400000
	s_addc_u32 s25, s17, 0
	s_and_b32 s28, s12, 7
	s_lshr_b32 s29, s12, 3
	s_lshl_b32 s29, s29, 1
	s_add_u32 s29, s29, s6
	s_lshr_b32 s30, s29, 3
	s_lshl_b32 s28, s28, 3
	s_add_u32 s30, s30, s28
	s_and_b32 s31, s29, 7
	s_lshl_b32 s33, s31, 17
	s_lshl_b32 s34, s30, 17
	v_lshlrev_b32_e32 v215, 11, v202
	v_lshl_add_u32 v215, v203, 4, v215
	v_add_u32_e32 v194, s33, v204
	v_add_u32_e32 v198, s34, v215
	v_add_u32_e32 v195, s33, v204
	v_add_u32_e32 v199, s34, v215
	v_add_u32_e32 v196, s33, v204
	v_add_u32_e32 v200, s34, v215
	v_add_u32_e32 v197, s33, v204
	v_add_u32_e32 v201, s34, v215
	v_add_u32_e32 v195, 0x8000, v195
	v_add_u32_e32 v199, 0x8000, v199
	v_add_u32_e32 v196, 0x10000, v196
	v_add_u32_e32 v200, 0x10000, v200
	v_add_u32_e32 v197, 0x18000, v197
	v_add_u32_e32 v201, 0x18000, v201
	s_lshl_b32 s33, s31, 19
	s_lshl_b32 s34, s30, 7
	s_add_u32 s33, s33, s34
	v_add_u32_e32 v209, s33, v208
	s_lshl_b32 s44, s4, 8
	s_add_u32 s44, s22, s44
	s_addc_u32 s45, s23, 0
	s_lshl_b32 s46, s4, 14
	s_add_i32 m0, s46, 0x0
	global_load_dwordx4 v[66:69], v194, s[20:21] offset:0
	global_load_dwordx4 v[70:73], v195, s[20:21] offset:0
	global_load_lds_dwordx4 v198, s[44:45]
	s_add_i32 m0, s46, 0x400
	global_load_dwordx4 v[74:77], v196, s[20:21] offset:0
	global_load_dwordx4 v[78:81], v197, s[20:21] offset:0
	global_load_lds_dwordx4 v199, s[44:45]
	s_add_i32 m0, s46, 0x800
	global_load_dwordx4 v[82:85], v194, s[20:21] offset:64
	global_load_dwordx4 v[86:89], v195, s[20:21] offset:64
	global_load_lds_dwordx4 v200, s[44:45]
	s_add_i32 m0, s46, 0xc00
	global_load_dwordx4 v[90:93], v196, s[20:21] offset:64
	global_load_dwordx4 v[94:97], v197, s[20:21] offset:64
	global_load_lds_dwordx4 v201, s[44:45]
	s_add_u32 s44, s44, 64
	s_addc_u32 s45, s45, 0
	s_add_i32 m0, s46, 0x1000
	global_load_dwordx4 v[98:101], v194, s[20:21] offset:128
	global_load_dwordx4 v[102:105], v195, s[20:21] offset:128
	global_load_lds_dwordx4 v198, s[44:45]
	s_add_i32 m0, s46, 0x1400
	global_load_dwordx4 v[106:109], v196, s[20:21] offset:128
	global_load_dwordx4 v[110:113], v197, s[20:21] offset:128
	global_load_lds_dwordx4 v199, s[44:45]
	s_add_i32 m0, s46, 0x1800
	global_load_dwordx4 v[114:117], v194, s[20:21] offset:192
	global_load_dwordx4 v[118:121], v195, s[20:21] offset:192
	global_load_lds_dwordx4 v200, s[44:45]
	s_add_i32 m0, s46, 0x1c00
	global_load_dwordx4 v[122:125], v196, s[20:21] offset:192
	global_load_dwordx4 v[126:129], v197, s[20:21] offset:192
	global_load_lds_dwordx4 v201, s[44:45]
	s_add_u32 s44, s44, 64
	s_addc_u32 s45, s45, 0
	s_add_i32 m0, s46, 0x2000
	global_load_dwordx4 v[130:133], v194, s[20:21] offset:256
	global_load_dwordx4 v[134:137], v195, s[20:21] offset:256
	global_load_lds_dwordx4 v198, s[44:45]
	s_add_i32 m0, s46, 0x2400
	global_load_dwordx4 v[138:141], v196, s[20:21] offset:256
	global_load_dwordx4 v[142:145], v197, s[20:21] offset:256
	global_load_lds_dwordx4 v199, s[44:45]
	s_add_i32 m0, s46, 0x2800
	global_load_dwordx4 v[146:149], v194, s[20:21] offset:320
	global_load_dwordx4 v[150:153], v195, s[20:21] offset:320
	global_load_lds_dwordx4 v200, s[44:45]
	s_add_i32 m0, s46, 0x2c00
	global_load_dwordx4 v[154:157], v196, s[20:21] offset:320
	global_load_dwordx4 v[158:161], v197, s[20:21] offset:320
	global_load_lds_dwordx4 v201, s[44:45]
	s_add_u32 s44, s44, 64
	s_addc_u32 s45, s45, 0
	s_add_i32 m0, s46, 0x3000
	global_load_dwordx4 v[162:165], v194, s[20:21] offset:384
	global_load_dwordx4 v[166:169], v195, s[20:21] offset:384
	global_load_lds_dwordx4 v198, s[44:45]
	s_add_i32 m0, s46, 0x3400
	global_load_dwordx4 v[170:173], v196, s[20:21] offset:384
	global_load_dwordx4 v[174:177], v197, s[20:21] offset:384
	global_load_lds_dwordx4 v199, s[44:45]
	s_add_i32 m0, s46, 0x3800
	global_load_dwordx4 v[178:181], v194, s[20:21] offset:448
	global_load_dwordx4 v[182:185], v195, s[20:21] offset:448
	global_load_lds_dwordx4 v200, s[44:45]
	s_add_i32 m0, s46, 0x3c00
	global_load_dwordx4 v[186:189], v196, s[20:21] offset:448
	global_load_dwordx4 v[190:193], v197, s[20:21] offset:448
	global_load_lds_dwordx4 v201, s[44:45]
	s_waitcnt vmcnt(0)
	s_barrier
	s_lshl_b32 s47, s5, 15
	v_lshl_add_u32 v214, v205, 4, s47
	ds_read_b128 v[218:221], v214 offset:0
	ds_read_b128 v[222:225], v214 offset:1024
	ds_read_b128 v[226:229], v214 offset:2048
	ds_read_b128 v[230:233], v214 offset:3072
	ds_read_b128 v[234:237], v214 offset:4096
	ds_read_b128 v[238:241], v214 offset:5120
	ds_read_b128 v[242:245], v214 offset:6144
	ds_read_b128 v[246:249], v214 offset:7168
	s_waitcnt lgkmcnt(4)
	v_mfma_f32_16x16x32_bf16 v[2:5], v[218:221], v[66:69], 0
	v_mfma_f32_16x16x32_bf16 v[6:9], v[222:225], v[66:69], 0
	v_mfma_f32_16x16x32_bf16 v[10:13], v[226:229], v[66:69], 0
	v_mfma_f32_16x16x32_bf16 v[14:17], v[230:233], v[66:69], 0
	v_mfma_f32_16x16x32_bf16 v[18:21], v[218:221], v[70:73], 0
	v_mfma_f32_16x16x32_bf16 v[22:25], v[222:225], v[70:73], 0
	v_mfma_f32_16x16x32_bf16 v[26:29], v[226:229], v[70:73], 0
	v_mfma_f32_16x16x32_bf16 v[30:33], v[230:233], v[70:73], 0
	v_mfma_f32_16x16x32_bf16 v[34:37], v[218:221], v[74:77], 0
	v_mfma_f32_16x16x32_bf16 v[38:41], v[222:225], v[74:77], 0
	v_mfma_f32_16x16x32_bf16 v[42:45], v[226:229], v[74:77], 0
	v_mfma_f32_16x16x32_bf16 v[46:49], v[230:233], v[74:77], 0
	v_mfma_f32_16x16x32_bf16 v[50:53], v[218:221], v[78:81], 0
	v_mfma_f32_16x16x32_bf16 v[54:57], v[222:225], v[78:81], 0
	v_mfma_f32_16x16x32_bf16 v[58:61], v[226:229], v[78:81], 0
	v_mfma_f32_16x16x32_bf16 v[62:65], v[230:233], v[78:81], 0
	ds_read_b128 v[218:221], v214 offset:8192
	ds_read_b128 v[222:225], v214 offset:9216
	ds_read_b128 v[226:229], v214 offset:10240
	ds_read_b128 v[230:233], v214 offset:11264
	s_waitcnt lgkmcnt(4)
	v_mfma_f32_16x16x32_bf16 v[2:5], v[234:237], v[82:85], v[2:5]
	v_mfma_f32_16x16x32_bf16 v[6:9], v[238:241], v[82:85], v[6:9]
	v_mfma_f32_16x16x32_bf16 v[10:13], v[242:245], v[82:85], v[10:13]
	v_mfma_f32_16x16x32_bf16 v[14:17], v[246:249], v[82:85], v[14:17]
	v_mfma_f32_16x16x32_bf16 v[18:21], v[234:237], v[86:89], v[18:21]
	v_mfma_f32_16x16x32_bf16 v[22:25], v[238:241], v[86:89], v[22:25]
	v_mfma_f32_16x16x32_bf16 v[26:29], v[242:245], v[86:89], v[26:29]
	v_mfma_f32_16x16x32_bf16 v[30:33], v[246:249], v[86:89], v[30:33]
	v_mfma_f32_16x16x32_bf16 v[34:37], v[234:237], v[90:93], v[34:37]
	v_mfma_f32_16x16x32_bf16 v[38:41], v[238:241], v[90:93], v[38:41]
	v_mfma_f32_16x16x32_bf16 v[42:45], v[242:245], v[90:93], v[42:45]
	v_mfma_f32_16x16x32_bf16 v[46:49], v[246:249], v[90:93], v[46:49]
	v_mfma_f32_16x16x32_bf16 v[50:53], v[234:237], v[94:97], v[50:53]
	v_mfma_f32_16x16x32_bf16 v[54:57], v[238:241], v[94:97], v[54:57]
	v_mfma_f32_16x16x32_bf16 v[58:61], v[242:245], v[94:97], v[58:61]
	v_mfma_f32_16x16x32_bf16 v[62:65], v[246:249], v[94:97], v[62:65]
	ds_read_b128 v[234:237], v214 offset:12288
	ds_read_b128 v[238:241], v214 offset:13312
	ds_read_b128 v[242:245], v214 offset:14336
	ds_read_b128 v[246:249], v214 offset:15360
	s_waitcnt lgkmcnt(4)
	v_mfma_f32_16x16x32_bf16 v[2:5], v[218:221], v[98:101], v[2:5]
	v_mfma_f32_16x16x32_bf16 v[6:9], v[222:225], v[98:101], v[6:9]
	v_mfma_f32_16x16x32_bf16 v[10:13], v[226:229], v[98:101], v[10:13]
	v_mfma_f32_16x16x32_bf16 v[14:17], v[230:233], v[98:101], v[14:17]
	v_mfma_f32_16x16x32_bf16 v[18:21], v[218:221], v[102:105], v[18:21]
	v_mfma_f32_16x16x32_bf16 v[22:25], v[222:225], v[102:105], v[22:25]
	v_mfma_f32_16x16x32_bf16 v[26:29], v[226:229], v[102:105], v[26:29]
	v_mfma_f32_16x16x32_bf16 v[30:33], v[230:233], v[102:105], v[30:33]
	v_mfma_f32_16x16x32_bf16 v[34:37], v[218:221], v[106:109], v[34:37]
	v_mfma_f32_16x16x32_bf16 v[38:41], v[222:225], v[106:109], v[38:41]
	v_mfma_f32_16x16x32_bf16 v[42:45], v[226:229], v[106:109], v[42:45]
	v_mfma_f32_16x16x32_bf16 v[46:49], v[230:233], v[106:109], v[46:49]
	v_mfma_f32_16x16x32_bf16 v[50:53], v[218:221], v[110:113], v[50:53]
	v_mfma_f32_16x16x32_bf16 v[54:57], v[222:225], v[110:113], v[54:57]
	v_mfma_f32_16x16x32_bf16 v[58:61], v[226:229], v[110:113], v[58:61]
	v_mfma_f32_16x16x32_bf16 v[62:65], v[230:233], v[110:113], v[62:65]
	ds_read_b128 v[218:221], v214 offset:16384
	ds_read_b128 v[222:225], v214 offset:17408
	ds_read_b128 v[226:229], v214 offset:18432
	ds_read_b128 v[230:233], v214 offset:19456
	s_waitcnt lgkmcnt(4)
	v_mfma_f32_16x16x32_bf16 v[2:5], v[234:237], v[114:117], v[2:5]
	v_mfma_f32_16x16x32_bf16 v[6:9], v[238:241], v[114:117], v[6:9]
	v_mfma_f32_16x16x32_bf16 v[10:13], v[242:245], v[114:117], v[10:13]
	v_mfma_f32_16x16x32_bf16 v[14:17], v[246:249], v[114:117], v[14:17]
	v_mfma_f32_16x16x32_bf16 v[18:21], v[234:237], v[118:121], v[18:21]
	v_mfma_f32_16x16x32_bf16 v[22:25], v[238:241], v[118:121], v[22:25]
	v_mfma_f32_16x16x32_bf16 v[26:29], v[242:245], v[118:121], v[26:29]
	v_mfma_f32_16x16x32_bf16 v[30:33], v[246:249], v[118:121], v[30:33]
	v_mfma_f32_16x16x32_bf16 v[34:37], v[234:237], v[122:125], v[34:37]
	v_mfma_f32_16x16x32_bf16 v[38:41], v[238:241], v[122:125], v[38:41]
	v_mfma_f32_16x16x32_bf16 v[42:45], v[242:245], v[122:125], v[42:45]
	v_mfma_f32_16x16x32_bf16 v[46:49], v[246:249], v[122:125], v[46:49]
	v_mfma_f32_16x16x32_bf16 v[50:53], v[234:237], v[126:129], v[50:53]
	v_mfma_f32_16x16x32_bf16 v[54:57], v[238:241], v[126:129], v[54:57]
	v_mfma_f32_16x16x32_bf16 v[58:61], v[242:245], v[126:129], v[58:61]
	v_mfma_f32_16x16x32_bf16 v[62:65], v[246:249], v[126:129], v[62:65]
	ds_read_b128 v[234:237], v214 offset:20480
	ds_read_b128 v[238:241], v214 offset:21504
	ds_read_b128 v[242:245], v214 offset:22528
	ds_read_b128 v[246:249], v214 offset:23552
	s_waitcnt lgkmcnt(4)
	v_mfma_f32_16x16x32_bf16 v[2:5], v[218:221], v[130:133], v[2:5]
	v_mfma_f32_16x16x32_bf16 v[6:9], v[222:225], v[130:133], v[6:9]
	v_mfma_f32_16x16x32_bf16 v[10:13], v[226:229], v[130:133], v[10:13]
	v_mfma_f32_16x16x32_bf16 v[14:17], v[230:233], v[130:133], v[14:17]
	v_mfma_f32_16x16x32_bf16 v[18:21], v[218:221], v[134:137], v[18:21]
	v_mfma_f32_16x16x32_bf16 v[22:25], v[222:225], v[134:137], v[22:25]
	v_mfma_f32_16x16x32_bf16 v[26:29], v[226:229], v[134:137], v[26:29]
	v_mfma_f32_16x16x32_bf16 v[30:33], v[230:233], v[134:137], v[30:33]
	v_mfma_f32_16x16x32_bf16 v[34:37], v[218:221], v[138:141], v[34:37]
	v_mfma_f32_16x16x32_bf16 v[38:41], v[222:225], v[138:141], v[38:41]
	v_mfma_f32_16x16x32_bf16 v[42:45], v[226:229], v[138:141], v[42:45]
	v_mfma_f32_16x16x32_bf16 v[46:49], v[230:233], v[138:141], v[46:49]
	v_mfma_f32_16x16x32_bf16 v[50:53], v[218:221], v[142:145], v[50:53]
	v_mfma_f32_16x16x32_bf16 v[54:57], v[222:225], v[142:145], v[54:57]
	v_mfma_f32_16x16x32_bf16 v[58:61], v[226:229], v[142:145], v[58:61]
	v_mfma_f32_16x16x32_bf16 v[62:65], v[230:233], v[142:145], v[62:65]
	ds_read_b128 v[218:221], v214 offset:24576
	ds_read_b128 v[222:225], v214 offset:25600
	ds_read_b128 v[226:229], v214 offset:26624
	ds_read_b128 v[230:233], v214 offset:27648
	s_waitcnt lgkmcnt(4)
	v_mfma_f32_16x16x32_bf16 v[2:5], v[234:237], v[146:149], v[2:5]
	v_mfma_f32_16x16x32_bf16 v[6:9], v[238:241], v[146:149], v[6:9]
	v_mfma_f32_16x16x32_bf16 v[10:13], v[242:245], v[146:149], v[10:13]
	v_mfma_f32_16x16x32_bf16 v[14:17], v[246:249], v[146:149], v[14:17]
	v_mfma_f32_16x16x32_bf16 v[18:21], v[234:237], v[150:153], v[18:21]
	v_mfma_f32_16x16x32_bf16 v[22:25], v[238:241], v[150:153], v[22:25]
	v_mfma_f32_16x16x32_bf16 v[26:29], v[242:245], v[150:153], v[26:29]
	v_mfma_f32_16x16x32_bf16 v[30:33], v[246:249], v[150:153], v[30:33]
	v_mfma_f32_16x16x32_bf16 v[34:37], v[234:237], v[154:157], v[34:37]
	v_mfma_f32_16x16x32_bf16 v[38:41], v[238:241], v[154:157], v[38:41]
	v_mfma_f32_16x16x32_bf16 v[42:45], v[242:245], v[154:157], v[42:45]
	v_mfma_f32_16x16x32_bf16 v[46:49], v[246:249], v[154:157], v[46:49]
	v_mfma_f32_16x16x32_bf16 v[50:53], v[234:237], v[158:161], v[50:53]
	v_mfma_f32_16x16x32_bf16 v[54:57], v[238:241], v[158:161], v[54:57]
	v_mfma_f32_16x16x32_bf16 v[58:61], v[242:245], v[158:161], v[58:61]
	v_mfma_f32_16x16x32_bf16 v[62:65], v[246:249], v[158:161], v[62:65]
	ds_read_b128 v[234:237], v214 offset:28672
	ds_read_b128 v[238:241], v214 offset:29696
	ds_read_b128 v[242:245], v214 offset:30720
	ds_read_b128 v[246:249], v214 offset:31744
	s_waitcnt lgkmcnt(4)
	v_mfma_f32_16x16x32_bf16 v[2:5], v[218:221], v[162:165], v[2:5]
	v_mfma_f32_16x16x32_bf16 v[6:9], v[222:225], v[162:165], v[6:9]
	v_mfma_f32_16x16x32_bf16 v[10:13], v[226:229], v[162:165], v[10:13]
	v_mfma_f32_16x16x32_bf16 v[14:17], v[230:233], v[162:165], v[14:17]
	v_mfma_f32_16x16x32_bf16 v[18:21], v[218:221], v[166:169], v[18:21]
	v_mfma_f32_16x16x32_bf16 v[22:25], v[222:225], v[166:169], v[22:25]
	v_mfma_f32_16x16x32_bf16 v[26:29], v[226:229], v[166:169], v[26:29]
	v_mfma_f32_16x16x32_bf16 v[30:33], v[230:233], v[166:169], v[30:33]
	v_mfma_f32_16x16x32_bf16 v[34:37], v[218:221], v[170:173], v[34:37]
	v_mfma_f32_16x16x32_bf16 v[38:41], v[222:225], v[170:173], v[38:41]
	v_mfma_f32_16x16x32_bf16 v[42:45], v[226:229], v[170:173], v[42:45]
	v_mfma_f32_16x16x32_bf16 v[46:49], v[230:233], v[170:173], v[46:49]
	v_mfma_f32_16x16x32_bf16 v[50:53], v[218:221], v[174:177], v[50:53]
	v_mfma_f32_16x16x32_bf16 v[54:57], v[222:225], v[174:177], v[54:57]
	v_mfma_f32_16x16x32_bf16 v[58:61], v[226:229], v[174:177], v[58:61]
	v_mfma_f32_16x16x32_bf16 v[62:65], v[230:233], v[174:177], v[62:65]
	s_waitcnt lgkmcnt(0)
	v_mfma_f32_16x16x32_bf16 v[2:5], v[234:237], v[178:181], v[2:5]
	v_mfma_f32_16x16x32_bf16 v[6:9], v[238:241], v[178:181], v[6:9]
	v_mfma_f32_16x16x32_bf16 v[10:13], v[242:245], v[178:181], v[10:13]
	v_mfma_f32_16x16x32_bf16 v[14:17], v[246:249], v[178:181], v[14:17]
	v_mfma_f32_16x16x32_bf16 v[18:21], v[234:237], v[182:185], v[18:21]
	v_mfma_f32_16x16x32_bf16 v[22:25], v[238:241], v[182:185], v[22:25]
	v_mfma_f32_16x16x32_bf16 v[26:29], v[242:245], v[182:185], v[26:29]
	v_mfma_f32_16x16x32_bf16 v[30:33], v[246:249], v[182:185], v[30:33]
	v_mfma_f32_16x16x32_bf16 v[34:37], v[234:237], v[186:189], v[34:37]
	v_mfma_f32_16x16x32_bf16 v[38:41], v[238:241], v[186:189], v[38:41]
	v_mfma_f32_16x16x32_bf16 v[42:45], v[242:245], v[186:189], v[42:45]
	v_mfma_f32_16x16x32_bf16 v[46:49], v[246:249], v[186:189], v[46:49]
	v_mfma_f32_16x16x32_bf16 v[50:53], v[234:237], v[190:193], v[50:53]
	v_mfma_f32_16x16x32_bf16 v[54:57], v[238:241], v[190:193], v[54:57]
	v_mfma_f32_16x16x32_bf16 v[58:61], v[242:245], v[190:193], v[58:61]
	v_mfma_f32_16x16x32_bf16 v[62:65], v[246:249], v[190:193], v[62:65]
	s_nop 7
	s_barrier
	ds_write_b128 v206, v[2:5] offset:0
	ds_write_b128 v206, v[6:9] offset:1024
	ds_write_b128 v206, v[10:13] offset:2048
	ds_write_b128 v206, v[14:17] offset:3072
	ds_write_b128 v206, v[18:21] offset:4096
	ds_write_b128 v206, v[22:25] offset:5120
	ds_write_b128 v206, v[26:29] offset:6144
	ds_write_b128 v206, v[30:33] offset:7168
	ds_write_b128 v206, v[34:37] offset:8192
	ds_write_b128 v206, v[38:41] offset:9216
	ds_write_b128 v206, v[42:45] offset:10240
	ds_write_b128 v206, v[46:49] offset:11264
	ds_write_b128 v206, v[50:53] offset:12288
	ds_write_b128 v206, v[54:57] offset:13312
	ds_write_b128 v206, v[58:61] offset:14336
	ds_write_b128 v206, v[62:65] offset:15360
	s_waitcnt lgkmcnt(0)
	s_barrier
	ds_read_b128 v[2:5], v207 offset:0
	ds_read_b128 v[6:9], v207 offset:16384
	ds_read_b128 v[10:13], v207 offset:32768
	ds_read_b128 v[14:17], v207 offset:49152
	ds_read_b128 v[18:21], v207 offset:1024
	ds_read_b128 v[22:25], v207 offset:17408
	ds_read_b128 v[26:29], v207 offset:33792
	ds_read_b128 v[30:33], v207 offset:50176
	ds_read_b128 v[34:37], v207 offset:2048
	ds_read_b128 v[38:41], v207 offset:18432
	ds_read_b128 v[42:45], v207 offset:34816
	ds_read_b128 v[46:49], v207 offset:51200
	ds_read_b128 v[50:53], v207 offset:3072
	ds_read_b128 v[54:57], v207 offset:19456
	ds_read_b128 v[58:61], v207 offset:35840
	ds_read_b128 v[62:65], v207 offset:52224
	s_waitcnt lgkmcnt(12)
	v_add_f32_e32 v2, v2, v6
	v_add_f32_e32 v3, v3, v7
	v_add_f32_e32 v4, v4, v8
	v_add_f32_e32 v5, v5, v9
	v_add_f32_e32 v10, v10, v14
	v_add_f32_e32 v11, v11, v15
	v_add_f32_e32 v12, v12, v16
	v_add_f32_e32 v13, v13, v17
	v_add_f32_e32 v2, v2, v10
	v_add_f32_e32 v3, v3, v11
	v_add_f32_e32 v4, v4, v12
	v_add_f32_e32 v5, v5, v13
	s_waitcnt lgkmcnt(8)
	v_add_f32_e32 v18, v18, v22
	v_add_f32_e32 v19, v19, v23
	v_add_f32_e32 v20, v20, v24
	v_add_f32_e32 v21, v21, v25
	v_add_f32_e32 v26, v26, v30
	v_add_f32_e32 v27, v27, v31
	v_add_f32_e32 v28, v28, v32
	v_add_f32_e32 v29, v29, v33
	v_add_f32_e32 v18, v18, v26
	v_add_f32_e32 v19, v19, v27
	v_add_f32_e32 v20, v20, v28
	v_add_f32_e32 v21, v21, v29
	s_waitcnt lgkmcnt(4)
	v_add_f32_e32 v34, v34, v38
	v_add_f32_e32 v35, v35, v39
	v_add_f32_e32 v36, v36, v40
	v_add_f32_e32 v37, v37, v41
	v_add_f32_e32 v42, v42, v46
	v_add_f32_e32 v43, v43, v47
	v_add_f32_e32 v44, v44, v48
	v_add_f32_e32 v45, v45, v49
	v_add_f32_e32 v34, v34, v42
	v_add_f32_e32 v35, v35, v43
	v_add_f32_e32 v36, v36, v44
	v_add_f32_e32 v37, v37, v45
	s_waitcnt lgkmcnt(0)
	v_add_f32_e32 v50, v50, v54
	v_add_f32_e32 v51, v51, v55
	v_add_f32_e32 v52, v52, v56
	v_add_f32_e32 v53, v53, v57
	v_add_f32_e32 v58, v58, v62
	v_add_f32_e32 v59, v59, v63
	v_add_f32_e32 v60, v60, v64
	v_add_f32_e32 v61, v61, v65
	v_add_f32_e32 v50, v50, v58
	v_add_f32_e32 v51, v51, v59
	v_add_f32_e32 v52, v52, v60
	v_add_f32_e32 v53, v53, v61
	v_max_f32_e32 v2, 0, v2
	v_max_f32_e32 v3, 0, v3
	v_max_f32_e32 v4, 0, v4
	v_max_f32_e32 v5, 0, v5
	v_mul_f32_e32 v2, v2, v2
	v_mul_f32_e32 v3, v3, v3
	v_mul_f32_e32 v4, v4, v4
	v_mul_f32_e32 v5, v5, v5
	v_cvt_pk_bf16_f32 v210, v2, v3
	v_cvt_pk_bf16_f32 v211, v4, v5
	global_store_dwordx2 v209, v[210:211], s[24:25] offset:0
	v_max_f32_e32 v18, 0, v18
	v_max_f32_e32 v19, 0, v19
	v_max_f32_e32 v20, 0, v20
	v_max_f32_e32 v21, 0, v21
	v_mul_f32_e32 v18, v18, v18
	v_mul_f32_e32 v19, v19, v19
	v_mul_f32_e32 v20, v20, v20
	v_mul_f32_e32 v21, v21, v21
	v_cvt_pk_bf16_f32 v212, v18, v19
	v_cvt_pk_bf16_f32 v213, v20, v21
	global_store_dwordx2 v209, v[212:213], s[24:25] offset:32
	v_max_f32_e32 v34, 0, v34
	v_max_f32_e32 v35, 0, v35
	v_max_f32_e32 v36, 0, v36
	v_max_f32_e32 v37, 0, v37
	v_mul_f32_e32 v34, v34, v34
	v_mul_f32_e32 v35, v35, v35
	v_mul_f32_e32 v36, v36, v36
	v_mul_f32_e32 v37, v37, v37
	v_cvt_pk_bf16_f32 v214, v34, v35
	v_cvt_pk_bf16_f32 v215, v36, v37
	global_store_dwordx2 v209, v[214:215], s[24:25] offset:64
	v_max_f32_e32 v50, 0, v50
	v_max_f32_e32 v51, 0, v51
	v_max_f32_e32 v52, 0, v52
	v_max_f32_e32 v53, 0, v53
	v_mul_f32_e32 v50, v50, v50
	v_mul_f32_e32 v51, v51, v51
	v_mul_f32_e32 v52, v52, v52
	v_mul_f32_e32 v53, v53, v53
	v_cvt_pk_bf16_f32 v216, v50, v51
	v_cvt_pk_bf16_f32 v217, v52, v53
	global_store_dwordx2 v209, v[216:217], s[24:25] offset:96
	s_barrier
	s_add_i32 s12, s12, s3
	s_cmpk_lt_u32 s12, 0x100
	s_cbranch_scc1 .Lsmp12_unit

	.amdhsa_kernel _Z10fwd_kernelILi12ELi13EEv4Args
		.amdhsa_group_segment_fixed_size 0
		.amdhsa_private_segment_fixed_size 0
		.amdhsa_kernarg_size 488
		.amdhsa_user_sgpr_count 2
		.amdhsa_user_sgpr_dispatch_ptr 0
		.amdhsa_user_sgpr_queue_ptr 0
		.amdhsa_user_sgpr_kernarg_segment_ptr 1
		.amdhsa_user_sgpr_dispatch_id 0
		.amdhsa_user_sgpr_kernarg_preload_length 0
		.amdhsa_user_sgpr_kernarg_preload_offset 0
		.amdhsa_user_sgpr_private_segment_size 0
		.amdhsa_uses_dynamic_stack 0
		.amdhsa_enable_private_segment 0
		.amdhsa_system_sgpr_workgroup_id_x 1
		.amdhsa_system_sgpr_workgroup_id_y 0
		.amdhsa_system_sgpr_workgroup_id_z 0
		.amdhsa_system_sgpr_workgroup_info 0
		.amdhsa_system_vgpr_workitem_id 0
		.amdhsa_next_free_vgpr 256
		.amdhsa_next_free_sgpr 62
		.amdhsa_accum_offset 256
		.amdhsa_reserve_vcc 1
		.amdhsa_float_round_mode_32 0
		.amdhsa_float_round_mode_16_64 0
		.amdhsa_float_denorm_mode_32 3
		.amdhsa_float_denorm_mode_16_64 3
		.amdhsa_dx10_clamp 1
		.amdhsa_ieee_mode 1
		.amdhsa_fp16_overflow 0
		.amdhsa_tg_split 0
		.amdhsa_exception_fp_ieee_invalid_op 0
		.amdhsa_exception_fp_denorm_src 0
		.amdhsa_exception_fp_ieee_div_zero 0
		.amdhsa_exception_fp_ieee_overflow 0
		.amdhsa_exception_fp_ieee_underflow 0
		.amdhsa_exception_fp_ieee_inexact 0
		.amdhsa_exception_int_div_zero 0
	.end_amdhsa_kernel

amdhsa.kernels:
  - .agpr_count:     0
    .args:
      - .offset:         0
        .size:           232
        .value_kind:     by_value
      - .offset:         232
        .size:           4
        .value_kind:     hidden_block_count_x
      - .offset:         236
        .size:           4
        .value_kind:     hidden_block_count_y
      - .offset:         240
        .size:           4
        .value_kind:     hidden_block_count_z
      - .offset:         244
        .size:           2
        .value_kind:     hidden_group_size_x
      - .offset:         246
        .size:           2
        .value_kind:     hidden_group_size_y
      - .offset:         248
        .size:           2
        .value_kind:     hidden_group_size_z
      - .offset:         250
        .size:           2
        .value_kind:     hidden_remainder_x
      - .offset:         252
        .size:           2
        .value_kind:     hidden_remainder_y
      - .offset:         254
        .size:           2
        .value_kind:     hidden_remainder_z
      - .offset:         272
        .size:           8
        .value_kind:     hidden_global_offset_x
      - .offset:         280
        .size:           8
        .value_kind:     hidden_global_offset_y
      - .offset:         288
        .size:           8
        .value_kind:     hidden_global_offset_z
      - .offset:         296
        .size:           2
        .value_kind:     hidden_grid_dims
      - .offset:         352
        .size:           4
        .value_kind:     hidden_dynamic_lds_size
    .group_segment_fixed_size: 0
    .kernarg_segment_align: 8
    .kernarg_segment_size: 488
    .language:       OpenCL C
    .language_version:
      - 2
      - 0
    .max_flat_workgroup_size: 512
    .name:           _Z10fwd_kernelILi0ELi1EEv4Args
    .private_segment_fixed_size: 0
    .sgpr_count:     106
    .sgpr_spill_count: 0
    .symbol:         _Z10fwd_kernelILi0ELi1EEv4Args.kd
    .uniform_work_group_size: 1
    .uses_dynamic_stack: false
    .vgpr_count:     224
    .vgpr_spill_count: 0
    .wavefront_size: 64
  - .agpr_count:     0
    .args:
      - .offset:         0
        .size:           232
        .value_kind:     by_value
      - .offset:         232
        .size:           4
        .value_kind:     hidden_block_count_x
      - .offset:         236
        .size:           4
        .value_kind:     hidden_block_count_y
      - .offset:         240
        .size:           4
        .value_kind:     hidden_block_count_z
      - .offset:         244
        .size:           2
        .value_kind:     hidden_group_size_x
      - .offset:         246
        .size:           2
        .value_kind:     hidden_group_size_y
      - .offset:         248
        .size:           2
        .value_kind:     hidden_group_size_z
      - .offset:         250
        .size:           2
        .value_kind:     hidden_remainder_x
      - .offset:         252
        .size:           2
        .value_kind:     hidden_remainder_y
      - .offset:         254
        .size:           2
        .value_kind:     hidden_remainder_z
      - .offset:         272
        .size:           8
        .value_kind:     hidden_global_offset_x
      - .offset:         280
        .size:           8
        .value_kind:     hidden_global_offset_y
      - .offset:         288
        .size:           8
        .value_kind:     hidden_global_offset_z
      - .offset:         296
        .size:           2
        .value_kind:     hidden_grid_dims
      - .offset:         352
        .size:           4
        .value_kind:     hidden_dynamic_lds_size
    .group_segment_fixed_size: 0
    .kernarg_segment_align: 8
    .kernarg_segment_size: 488
    .language:       OpenCL C
    .language_version:
      - 2
      - 0
    .max_flat_workgroup_size: 512
    .name:           _Z10fwd_kernelILi1ELi2EEv4Args
    .private_segment_fixed_size: 0
    .sgpr_count:     64
    .sgpr_spill_count: 0
    .symbol:         _Z10fwd_kernelILi1ELi2EEv4Args.kd
    .uniform_work_group_size: 1
    .uses_dynamic_stack: false
    .vgpr_count:     256
    .vgpr_spill_count: 0
    .wavefront_size: 64
  - .agpr_count:     0
    .args:
      - .offset:         0
        .size:           232
        .value_kind:     by_value
      - .offset:         232
        .size:           4
        .value_kind:     hidden_block_count_x
      - .offset:         236
        .size:           4
        .value_kind:     hidden_block_count_y
      - .offset:         240
        .size:           4
        .value_kind:     hidden_block_count_z
      - .offset:         244
        .size:           2
        .value_kind:     hidden_group_size_x
      - .offset:         246
        .size:           2
        .value_kind:     hidden_group_size_y
      - .offset:         248
        .size:           2
        .value_kind:     hidden_group_size_z
      - .offset:         250
        .size:           2
        .value_kind:     hidden_remainder_x
      - .offset:         252
        .size:           2
        .value_kind:     hidden_remainder_y
      - .offset:         254
        .size:           2
        .value_kind:     hidden_remainder_z
      - .offset:         272
        .size:           8
        .value_kind:     hidden_global_offset_x
      - .offset:         280
        .size:           8
        .value_kind:     hidden_global_offset_y
      - .offset:         288
        .size:           8
        .value_kind:     hidden_global_offset_z
      - .offset:         296
        .size:           2
        .value_kind:     hidden_grid_dims
      - .offset:         352
        .size:           4
        .value_kind:     hidden_dynamic_lds_size
    .group_segment_fixed_size: 0
    .kernarg_segment_align: 8
    .kernarg_segment_size: 488
    .language:       OpenCL C
    .language_version:
      - 2
      - 0
    .max_flat_workgroup_size: 512
    .name:           _Z10fwd_kernelILi2ELi3EEv4Args
    .private_segment_fixed_size: 0
    .sgpr_count:     106
    .sgpr_spill_count: 11
    .symbol:         _Z10fwd_kernelILi2ELi3EEv4Args.kd
    .uniform_work_group_size: 1
    .uses_dynamic_stack: false
    .vgpr_count:     252
    .vgpr_spill_count: 0
    .wavefront_size: 64
  - .agpr_count:     0
    .args:
      - .offset:         0
        .size:           232
        .value_kind:     by_value
      - .offset:         232
        .size:           4
        .value_kind:     hidden_block_count_x
      - .offset:         236
        .size:           4
        .value_kind:     hidden_block_count_y
      - .offset:         240
        .size:           4
        .value_kind:     hidden_block_count_z
      - .offset:         244
        .size:           2
        .value_kind:     hidden_group_size_x
      - .offset:         246
        .size:           2
        .value_kind:     hidden_group_size_y
      - .offset:         248
        .size:           2
        .value_kind:     hidden_group_size_z
      - .offset:         250
        .size:           2
        .value_kind:     hidden_remainder_x
      - .offset:         252
        .size:           2
        .value_kind:     hidden_remainder_y
      - .offset:         254
        .size:           2
        .value_kind:     hidden_remainder_z
      - .offset:         272
        .size:           8
        .value_kind:     hidden_global_offset_x
      - .offset:         280
        .size:           8
        .value_kind:     hidden_global_offset_y
      - .offset:         288
        .size:           8
        .value_kind:     hidden_global_offset_z
      - .offset:         296
        .size:           2
        .value_kind:     hidden_grid_dims
      - .offset:         352
        .size:           4
        .value_kind:     hidden_dynamic_lds_size
    .group_segment_fixed_size: 0
    .kernarg_segment_align: 8
    .kernarg_segment_size: 488
    .language:       OpenCL C
    .language_version:
      - 2
      - 0
    .max_flat_workgroup_size: 512
    .name:           _Z10fwd_kernelILi3ELi4EEv4Args
    .private_segment_fixed_size: 0
    .sgpr_count:     67
    .sgpr_spill_count: 0
    .symbol:         _Z10fwd_kernelILi3ELi4EEv4Args.kd
    .uniform_work_group_size: 1
    .uses_dynamic_stack: false
    .vgpr_count:     240
    .vgpr_spill_count: 0
    .wavefront_size: 64
  - .agpr_count:     0
    .args:
      - .offset:         0
        .size:           232
        .value_kind:     by_value
      - .offset:         232
        .size:           4
        .value_kind:     hidden_block_count_x
      - .offset:         236
        .size:           4
        .value_kind:     hidden_block_count_y
      - .offset:         240
        .size:           4
        .value_kind:     hidden_block_count_z
      - .offset:         244
        .size:           2
        .value_kind:     hidden_group_size_x
      - .offset:         246
        .size:           2
        .value_kind:     hidden_group_size_y
      - .offset:         248
        .size:           2
        .value_kind:     hidden_group_size_z
      - .offset:         250
        .size:           2
        .value_kind:     hidden_remainder_x
      - .offset:         252
        .size:           2
        .value_kind:     hidden_remainder_y
      - .offset:         254
        .size:           2
        .value_kind:     hidden_remainder_z
      - .offset:         272
        .size:           8
        .value_kind:     hidden_global_offset_x
      - .offset:         280
        .size:           8
        .value_kind:     hidden_global_offset_y
      - .offset:         288
        .size:           8
        .value_kind:     hidden_global_offset_z
      - .offset:         296
        .size:           2
        .value_kind:     hidden_grid_dims
    .group_segment_fixed_size: 0
    .kernarg_segment_align: 8
    .kernarg_segment_size: 488
    .language:       OpenCL C
    .language_version:
      - 2
      - 0
    .max_flat_workgroup_size: 512
    .name:           _Z10fwd_kernelILi4ELi5EEv4Args
    .private_segment_fixed_size: 0
    .sgpr_count:     66
    .sgpr_spill_count: 0
    .symbol:         _Z10fwd_kernelILi4ELi5EEv4Args.kd
    .uniform_work_group_size: 1
    .uses_dynamic_stack: false
    .vgpr_count:     256
    .vgpr_spill_count: 0
    .wavefront_size: 64
  - .agpr_count:     0
    .args:
      - .offset:         0
        .size:           232
        .value_kind:     by_value
      - .offset:         232
        .size:           4
        .value_kind:     hidden_block_count_x
      - .offset:         236
        .size:           4
        .value_kind:     hidden_block_count_y
      - .offset:         240
        .size:           4
        .value_kind:     hidden_block_count_z
      - .offset:         244
        .size:           2
        .value_kind:     hidden_group_size_x
      - .offset:         246
        .size:           2
        .value_kind:     hidden_group_size_y
      - .offset:         248
        .size:           2
        .value_kind:     hidden_group_size_z
      - .offset:         250
        .size:           2
        .value_kind:     hidden_remainder_x
      - .offset:         252
        .size:           2
        .value_kind:     hidden_remainder_y
      - .offset:         254
        .size:           2
        .value_kind:     hidden_remainder_z
      - .offset:         272
        .size:           8
        .value_kind:     hidden_global_offset_x
      - .offset:         280
        .size:           8
        .value_kind:     hidden_global_offset_y
      - .offset:         288
        .size:           8
        .value_kind:     hidden_global_offset_z
      - .offset:         296
        .size:           2
        .value_kind:     hidden_grid_dims
      - .offset:         352
        .size:           4
        .value_kind:     hidden_dynamic_lds_size
    .group_segment_fixed_size: 0
    .kernarg_segment_align: 8
    .kernarg_segment_size: 488
    .language:       OpenCL C
    .language_version:
      - 2
      - 0
    .max_flat_workgroup_size: 512
    .name:           _Z10fwd_kernelILi5ELi6EEv4Args
    .private_segment_fixed_size: 0
    .sgpr_count:     68
    .sgpr_spill_count: 0
    .symbol:         _Z10fwd_kernelILi5ELi6EEv4Args.kd
    .uniform_work_group_size: 1
    .uses_dynamic_stack: false
    .vgpr_count:     256
    .vgpr_spill_count: 0
    .wavefront_size: 64
  - .agpr_count:     0
    .args:
      - .offset:         0
        .size:           232
        .value_kind:     by_value
      - .offset:         232
        .size:           4
        .value_kind:     hidden_block_count_x
      - .offset:         236
        .size:           4
        .value_kind:     hidden_block_count_y
      - .offset:         240
        .size:           4
        .value_kind:     hidden_block_count_z
      - .offset:         244
        .size:           2
        .value_kind:     hidden_group_size_x
      - .offset:         246
        .size:           2
        .value_kind:     hidden_group_size_y
      - .offset:         248
        .size:           2
        .value_kind:     hidden_group_size_z
      - .offset:         250
        .size:           2
        .value_kind:     hidden_remainder_x
      - .offset:         252
        .size:           2
        .value_kind:     hidden_remainder_y
      - .offset:         254
        .size:           2
        .value_kind:     hidden_remainder_z
      - .offset:         272
        .size:           8
        .value_kind:     hidden_global_offset_x
      - .offset:         280
        .size:           8
        .value_kind:     hidden_global_offset_y
      - .offset:         288
        .size:           8
        .value_kind:     hidden_global_offset_z
      - .offset:         296
        .size:           2
        .value_kind:     hidden_grid_dims
      - .offset:         352
        .size:           4
        .value_kind:     hidden_dynamic_lds_size
    .group_segment_fixed_size: 0
    .kernarg_segment_align: 8
    .kernarg_segment_size: 488
    .language:       OpenCL C
    .language_version:
      - 2
      - 0
    .max_flat_workgroup_size: 512
    .name:           _Z10fwd_kernelILi6ELi7EEv4Args
    .private_segment_fixed_size: 0
    .sgpr_count:     67
    .sgpr_spill_count: 0
    .symbol:         _Z10fwd_kernelILi6ELi7EEv4Args.kd
    .uniform_work_group_size: 1
    .uses_dynamic_stack: false
    .vgpr_count:     240
    .vgpr_spill_count: 0
    .wavefront_size: 64
  - .agpr_count:     0
    .args:
      - .offset:         0
        .size:           232
        .value_kind:     by_value
      - .offset:         232
        .size:           4
        .value_kind:     hidden_block_count_x
      - .offset:         236
        .size:           4
        .value_kind:     hidden_block_count_y
      - .offset:         240
        .size:           4
        .value_kind:     hidden_block_count_z
      - .offset:         244
        .size:           2
        .value_kind:     hidden_group_size_x
      - .offset:         246
        .size:           2
        .value_kind:     hidden_group_size_y
      - .offset:         248
        .size:           2
        .value_kind:     hidden_group_size_z
      - .offset:         250
        .size:           2
        .value_kind:     hidden_remainder_x
      - .offset:         252
        .size:           2
        .value_kind:     hidden_remainder_y
      - .offset:         254
        .size:           2
        .value_kind:     hidden_remainder_z
      - .offset:         272
        .size:           8
        .value_kind:     hidden_global_offset_x
      - .offset:         280
        .size:           8
        .value_kind:     hidden_global_offset_y
      - .offset:         288
        .size:           8
        .value_kind:     hidden_global_offset_z
      - .offset:         296
        .size:           2
        .value_kind:     hidden_grid_dims
    .group_segment_fixed_size: 0
    .kernarg_segment_align: 8
    .kernarg_segment_size: 488
    .language:       OpenCL C
    .language_version:
      - 2
      - 0
    .max_flat_workgroup_size: 512
    .name:           _Z10fwd_kernelILi7ELi8EEv4Args
    .private_segment_fixed_size: 0
    .sgpr_count:     66
    .sgpr_spill_count: 0
    .symbol:         _Z10fwd_kernelILi7ELi8EEv4Args.kd
    .uniform_work_group_size: 1
    .uses_dynamic_stack: false
    .vgpr_count:     256
    .vgpr_spill_count: 0
    .wavefront_size: 64
  - .agpr_count:     0
    .args:
      - .offset:         0
        .size:           232
        .value_kind:     by_value
      - .offset:         232
        .size:           4
        .value_kind:     hidden_block_count_x
      - .offset:         236
        .size:           4
        .value_kind:     hidden_block_count_y
      - .offset:         240
        .size:           4
        .value_kind:     hidden_block_count_z
      - .offset:         244
        .size:           2
        .value_kind:     hidden_group_size_x
      - .offset:         246
        .size:           2
        .value_kind:     hidden_group_size_y
      - .offset:         248
        .size:           2
        .value_kind:     hidden_group_size_z
      - .offset:         250
        .size:           2
        .value_kind:     hidden_remainder_x
      - .offset:         252
        .size:           2
        .value_kind:     hidden_remainder_y
      - .offset:         254
        .size:           2
        .value_kind:     hidden_remainder_z
      - .offset:         272
        .size:           8
        .value_kind:     hidden_global_offset_x
      - .offset:         280
        .size:           8
        .value_kind:     hidden_global_offset_y
      - .offset:         288
        .size:           8
        .value_kind:     hidden_global_offset_z
      - .offset:         296
        .size:           2
        .value_kind:     hidden_grid_dims
      - .offset:         352
        .size:           4
        .value_kind:     hidden_dynamic_lds_size
    .group_segment_fixed_size: 0
    .kernarg_segment_align: 8
    .kernarg_segment_size: 488
    .language:       OpenCL C
    .language_version:
      - 2
      - 0
    .max_flat_workgroup_size: 512
    .name:           _Z10fwd_kernelILi8ELi9EEv4Args
    .private_segment_fixed_size: 0
    .sgpr_count:     75
    .sgpr_spill_count: 0
    .symbol:         _Z10fwd_kernelILi8ELi9EEv4Args.kd
    .uniform_work_group_size: 1
    .uses_dynamic_stack: false
    .vgpr_count:     256
    .vgpr_spill_count: 0
    .wavefront_size: 64
  - .agpr_count:     0
    .args:
      - .offset:         0
        .size:           232
        .value_kind:     by_value
      - .offset:         232
        .size:           4
        .value_kind:     hidden_block_count_x
      - .offset:         236
        .size:           4
        .value_kind:     hidden_block_count_y
      - .offset:         240
        .size:           4
        .value_kind:     hidden_block_count_z
      - .offset:         244
        .size:           2
        .value_kind:     hidden_group_size_x
      - .offset:         246
        .size:           2
        .value_kind:     hidden_group_size_y
      - .offset:         248
        .size:           2
        .value_kind:     hidden_group_size_z
      - .offset:         250
        .size:           2
        .value_kind:     hidden_remainder_x
      - .offset:         252
        .size:           2
        .value_kind:     hidden_remainder_y
      - .offset:         254
        .size:           2
        .value_kind:     hidden_remainder_z
      - .offset:         272
        .size:           8
        .value_kind:     hidden_global_offset_x
      - .offset:         280
        .size:           8
        .value_kind:     hidden_global_offset_y
      - .offset:         288
        .size:           8
        .value_kind:     hidden_global_offset_z
      - .offset:         296
        .size:           2
        .value_kind:     hidden_grid_dims
      - .offset:         352
        .size:           4
        .value_kind:     hidden_dynamic_lds_size
    .group_segment_fixed_size: 0
    .kernarg_segment_align: 8
    .kernarg_segment_size: 488
    .language:       OpenCL C
    .language_version:
      - 2
      - 0
    .max_flat_workgroup_size: 512
    .name:           _Z10fwd_kernelILi9ELi10EEv4Args
    .private_segment_fixed_size: 0
    .sgpr_count:     82
    .sgpr_spill_count: 0
    .symbol:         _Z10fwd_kernelILi9ELi10EEv4Args.kd
    .uniform_work_group_size: 1
    .uses_dynamic_stack: false
    .vgpr_count:     200
    .vgpr_spill_count: 0
    .wavefront_size: 64
  - .agpr_count:     0
    .args:
      - .offset:         0
        .size:           232
        .value_kind:     by_value
      - .offset:         232
        .size:           4
        .value_kind:     hidden_block_count_x
      - .offset:         236
        .size:           4
        .value_kind:     hidden_block_count_y
      - .offset:         240
        .size:           4
        .value_kind:     hidden_block_count_z
      - .offset:         244
        .size:           2
        .value_kind:     hidden_group_size_x
      - .offset:         246
        .size:           2
        .value_kind:     hidden_group_size_y
      - .offset:         248
        .size:           2
        .value_kind:     hidden_group_size_z
      - .offset:         250
        .size:           2
        .value_kind:     hidden_remainder_x
      - .offset:         252
        .size:           2
        .value_kind:     hidden_remainder_y
      - .offset:         254
        .size:           2
        .value_kind:     hidden_remainder_z
      - .offset:         272
        .size:           8
        .value_kind:     hidden_global_offset_x
      - .offset:         280
        .size:           8
        .value_kind:     hidden_global_offset_y
      - .offset:         288
        .size:           8
        .value_kind:     hidden_global_offset_z
      - .offset:         296
        .size:           2
        .value_kind:     hidden_grid_dims
      - .offset:         352
        .size:           4
        .value_kind:     hidden_dynamic_lds_size
    .group_segment_fixed_size: 0
    .kernarg_segment_align: 8
    .kernarg_segment_size: 488
    .language:       OpenCL C
    .language_version:
      - 2
      - 0
    .max_flat_workgroup_size: 512
    .name:           _Z10fwd_kernelILi10ELi11EEv4Args
    .private_segment_fixed_size: 0
    .sgpr_count:     67
    .sgpr_spill_count: 0
    .symbol:         _Z10fwd_kernelILi10ELi11EEv4Args.kd
    .uniform_work_group_size: 1
    .uses_dynamic_stack: false
    .vgpr_count:     240
    .vgpr_spill_count: 0
    .wavefront_size: 64
  - .agpr_count:     0
    .args:
      - .offset:         0
        .size:           232
        .value_kind:     by_value
      - .offset:         232
        .size:           4
        .value_kind:     hidden_block_count_x
      - .offset:         236
        .size:           4
        .value_kind:     hidden_block_count_y
      - .offset:         240
        .size:           4
        .value_kind:     hidden_block_count_z
      - .offset:         244
        .size:           2
        .value_kind:     hidden_group_size_x
      - .offset:         246
        .size:           2
        .value_kind:     hidden_group_size_y
      - .offset:         248
        .size:           2
        .value_kind:     hidden_group_size_z
      - .offset:         250
        .size:           2
        .value_kind:     hidden_remainder_x
      - .offset:         252
        .size:           2
        .value_kind:     hidden_remainder_y
      - .offset:         254
        .size:           2
        .value_kind:     hidden_remainder_z
      - .offset:         272
        .size:           8
        .value_kind:     hidden_global_offset_x
      - .offset:         280
        .size:           8
        .value_kind:     hidden_global_offset_y
      - .offset:         288
        .size:           8
        .value_kind:     hidden_global_offset_z
      - .offset:         296
        .size:           2
        .value_kind:     hidden_grid_dims
    .group_segment_fixed_size: 0
    .kernarg_segment_align: 8
    .kernarg_segment_size: 488
    .language:       OpenCL C
    .language_version:
      - 2
      - 0
    .max_flat_workgroup_size: 512
    .name:           _Z10fwd_kernelILi11ELi12EEv4Args
    .private_segment_fixed_size: 0
    .sgpr_count:     66
    .sgpr_spill_count: 0
    .symbol:         _Z10fwd_kernelILi11ELi12EEv4Args.kd
    .uniform_work_group_size: 1
    .uses_dynamic_stack: false
    .vgpr_count:     256
    .vgpr_spill_count: 0
    .wavefront_size: 64
  - .agpr_count:     0
    .args:
      - .offset:         0
        .size:           232
        .value_kind:     by_value
      - .offset:         232
        .size:           4
        .value_kind:     hidden_block_count_x
      - .offset:         236
        .size:           4
        .value_kind:     hidden_block_count_y
      - .offset:         240
        .size:           4
        .value_kind:     hidden_block_count_z
      - .offset:         244
        .size:           2
        .value_kind:     hidden_group_size_x
      - .offset:         246
        .size:           2
        .value_kind:     hidden_group_size_y
      - .offset:         248
        .size:           2
        .value_kind:     hidden_group_size_z
      - .offset:         250
        .size:           2
        .value_kind:     hidden_remainder_x
      - .offset:         252
        .size:           2
        .value_kind:     hidden_remainder_y
      - .offset:         254
        .size:           2
        .value_kind:     hidden_remainder_z
      - .offset:         272
        .size:           8
        .value_kind:     hidden_global_offset_x
      - .offset:         280
        .size:           8
        .value_kind:     hidden_global_offset_y
      - .offset:         288
        .size:           8
        .value_kind:     hidden_global_offset_z
      - .offset:         296
        .size:           2
        .value_kind:     hidden_grid_dims
      - .offset:         352
        .size:           4
        .value_kind:     hidden_dynamic_lds_size
    .group_segment_fixed_size: 0
    .kernarg_segment_align: 8
    .kernarg_segment_size: 488
    .language:       OpenCL C
    .language_version:
      - 2
      - 0
    .max_flat_workgroup_size: 512
    .name:           _Z10fwd_kernelILi12ELi13EEv4Args
    .private_segment_fixed_size: 0
    .sgpr_count:     68
    .sgpr_spill_count: 0
    .symbol:         _Z10fwd_kernelILi12ELi13EEv4Args.kd
    .uniform_work_group_size: 1
    .uses_dynamic_stack: false
    .vgpr_count:     256
    .vgpr_spill_count: 0
    .wavefront_size: 64
  - .agpr_count:     0
    .args:
      - .offset:         0
        .size:           232
        .value_kind:     by_value
      - .offset:         232
        .size:           4
        .value_kind:     hidden_block_count_x
      - .offset:         236
        .size:           4
        .value_kind:     hidden_block_count_y
      - .offset:         240
        .size:           4
        .value_kind:     hidden_block_count_z
      - .offset:         244
        .size:           2
        .value_kind:     hidden_group_size_x
      - .offset:         246
        .size:           2
        .value_kind:     hidden_group_size_y
      - .offset:         248
        .size:           2
        .value_kind:     hidden_group_size_z
      - .offset:         250
        .size:           2
        .value_kind:     hidden_remainder_x
      - .offset:         252
        .size:           2
        .value_kind:     hidden_remainder_y
      - .offset:         254
        .size:           2
        .value_kind:     hidden_remainder_z
      - .offset:         272
        .size:           8
        .value_kind:     hidden_global_offset_x
      - .offset:         280
        .size:           8
        .value_kind:     hidden_global_offset_y
      - .offset:         288
        .size:           8
        .value_kind:     hidden_global_offset_z
      - .offset:         296
        .size:           2
        .value_kind:     hidden_grid_dims
      - .offset:         352
        .size:           4
        .value_kind:     hidden_dynamic_lds_size
    .group_segment_fixed_size: 0
    .kernarg_segment_align: 8
    .kernarg_segment_size: 488
    .language:       OpenCL C
    .language_version:
      - 2
      - 0
    .max_flat_workgroup_size: 512
    .name:           _Z10fwd_kernelILi13ELi14EEv4Args
    .private_segment_fixed_size: 0
    .sgpr_count:     67
    .sgpr_spill_count: 0
    .symbol:         _Z10fwd_kernelILi13ELi14EEv4Args.kd
    .uniform_work_group_size: 1
    .uses_dynamic_stack: false
    .vgpr_count:     240
    .vgpr_spill_count: 0
    .wavefront_size: 64
  - .agpr_count:     0
    .args:
      - .offset:         0
        .size:           232
        .value_kind:     by_value
      - .offset:         232
        .size:           4
        .value_kind:     hidden_block_count_x
      - .offset:         236
        .size:           4
        .value_kind:     hidden_block_count_y
      - .offset:         240
        .size:           4
        .value_kind:     hidden_block_count_z
      - .offset:         244
        .size:           2
        .value_kind:     hidden_group_size_x
      - .offset:         246
        .size:           2
        .value_kind:     hidden_group_size_y
      - .offset:         248
        .size:           2
        .value_kind:     hidden_group_size_z
      - .offset:         250
        .size:           2
        .value_kind:     hidden_remainder_x
      - .offset:         252
        .size:           2
        .value_kind:     hidden_remainder_y
      - .offset:         254
        .size:           2
        .value_kind:     hidden_remainder_z
      - .offset:         272
        .size:           8
        .value_kind:     hidden_global_offset_x
      - .offset:         280
        .size:           8
        .value_kind:     hidden_global_offset_y
      - .offset:         288
        .size:           8
        .value_kind:     hidden_global_offset_z
      - .offset:         296
        .size:           2
        .value_kind:     hidden_grid_dims
    .group_segment_fixed_size: 0
    .kernarg_segment_align: 8
    .kernarg_segment_size: 488
    .language:       OpenCL C
    .language_version:
      - 2
      - 0
    .max_flat_workgroup_size: 512
    .name:           _Z10fwd_kernelILi14ELi15EEv4Args
    .private_segment_fixed_size: 0
    .sgpr_count:     66
    .sgpr_spill_count: 0
    .symbol:         _Z10fwd_kernelILi14ELi15EEv4Args.kd
    .uniform_work_group_size: 1
    .uses_dynamic_stack: false
    .vgpr_count:     256
    .vgpr_spill_count: 0
    .wavefront_size: 64
